# EpiResid residual-stream f32 stores made write-through (sc1) so they do not occupy L2
# speedup vs baseline: 1.0039x; 1.0039x over previous
.LBB0_475:
	s_waitcnt lgkmcnt(0)
	v_ashrrev_i32_e32 v139, 31, v138
	v_mov_b32_e32 v143, v133
	v_lshlrev_b64 v[146:147], 12, v[138:139]
	v_lshlrev_b64 v[158:159], 12, v[142:143]
	v_lshl_add_u64 v[156:157], s[12:13], 0, v[146:147]
	v_lshl_add_u64 v[158:159], s[14:15], 0, v[158:159]
	v_cmp_gt_i32_e32 vcc, s66, v138
	v_lshlrev_b64 v[144:145], 2, v[140:141]
	v_lshlrev_b64 v[160:161], 11, v[138:139]
	v_cndmask_b32_e32 v157, v159, v157, vcc
	v_cndmask_b32_e32 v156, v158, v156, vcc
	v_lshl_add_u64 v[168:169], v[156:157], 0, v[144:145]
	global_load_dwordx4 v[156:159], v[168:169], off
	global_load_dwordx4 v[184:187], v[168:169], off offset:64
	global_load_dwordx4 v[188:191], v[168:169], off offset:512
	global_load_dwordx4 v[192:195], v[168:169], off offset:576
	v_lshl_add_u64 v[146:147], s[20:21], 0, v[146:147]
	v_lshl_add_u64 v[160:161], s[26:27], 0, v[160:161]
	v_lshl_add_u64 v[172:173], v[146:147], 0, v[144:145]
	v_lshl_add_u64 v[174:175], v[140:141], 1, v[160:161]
	v_and_b32_e32 v143, 64, v154
	v_xor_b32_e32 v132, 16, v154
	s_waitcnt vmcnt(3) lgkmcnt(0)
	v_pk_fma_f32 v[158:159], v[126:127], 0.5, v[158:159] op_sel_hi:[1,0,1]
	v_pk_fma_f32 v[156:157], v[124:125], 0.5, v[156:157] op_sel_hi:[1,0,1]
	global_store_dwordx4 v[172:173], v[156:159], off sc1
	v_cvt_pk_bf16_f32 v146, v156, v157
	v_cvt_pk_bf16_f32 v147, v158, v159
	global_store_dwordx2 v[174:175], v[146:147], off
	s_waitcnt vmcnt(4) lgkmcnt(0)
	v_pk_fma_f32 v[186:187], v[122:123], 0.5, v[186:187] op_sel_hi:[1,0,1]
	v_pk_fma_f32 v[184:185], v[120:121], 0.5, v[184:185] op_sel_hi:[1,0,1]
	global_store_dwordx4 v[172:173], v[184:187], off offset:64 sc1
	v_cvt_pk_bf16_f32 v146, v184, v185
	v_cvt_pk_bf16_f32 v147, v186, v187
	global_store_dwordx2 v[174:175], v[146:147], off offset:32
	v_mul_f32_e32 v155, v187, v187
	v_fmac_f32_e32 v155, v186, v186
	s_waitcnt vmcnt(5) lgkmcnt(0)
	v_pk_fma_f32 v[190:191], v[118:119], 0.5, v[190:191] op_sel_hi:[1,0,1]
	v_pk_fma_f32 v[188:189], v[116:117], 0.5, v[188:189] op_sel_hi:[1,0,1]
	global_store_dwordx4 v[172:173], v[188:191], off offset:512 sc1
	v_cvt_pk_bf16_f32 v146, v188, v189
	v_cvt_pk_bf16_f32 v147, v190, v191
	global_store_dwordx2 v[174:175], v[146:147], off offset:256
	v_add_u32_e32 v146, 64, v143
	v_cmp_lt_i32_e32 vcc, v132, v146
	v_mul_f32_e32 v147, v159, v159
	v_fmac_f32_e32 v147, v158, v158
	v_cndmask_b32_e32 v132, v154, v132, vcc
	v_lshlrev_b32_e32 v143, 2, v132
	v_mul_f32_e32 v132, v157, v157
	v_fmac_f32_e32 v132, v156, v156
	v_add_f32_e32 v132, v132, v147
	v_mul_f32_e32 v147, v185, v185
	v_fmac_f32_e32 v147, v184, v184
	v_add_f32_e32 v147, v147, v155
	v_add_f32_e32 v132, v132, v147
	v_mul_f32_e32 v147, v189, v189
	v_mul_f32_e32 v155, v191, v191
	v_fmac_f32_e32 v147, v188, v188
	v_fmac_f32_e32 v155, v190, v190
	v_add_f32_e32 v147, v147, v155
	v_add_f32_e32 v132, v132, v147
	s_waitcnt vmcnt(6) lgkmcnt(0)
	v_pk_fma_f32 v[158:159], v[114:115], 0.5, v[194:195] op_sel_hi:[1,0,1]
	v_pk_fma_f32 v[156:157], v[112:113], 0.5, v[192:193] op_sel_hi:[1,0,1]
	v_mul_f32_e32 v155, v159, v159
	v_mul_f32_e32 v147, v157, v157
	v_fmac_f32_e32 v147, v156, v156
	v_fmac_f32_e32 v155, v158, v158
	v_add_f32_e32 v147, v147, v155
	v_add_f32_e32 v132, v132, v147
	ds_bpermute_b32 v147, v143, v132
	v_xor_b32_e32 v155, 32, v154
	v_cmp_lt_i32_e32 vcc, v155, v146
	global_store_dwordx4 v[172:173], v[156:159], off offset:576 sc1
	s_waitcnt lgkmcnt(0)
	v_add_f32_e32 v132, v132, v147
	v_cndmask_b32_e32 v146, v154, v155, vcc
	v_lshlrev_b32_e32 v155, 2, v146
	ds_bpermute_b32 v146, v155, v132
	v_cvt_pk_bf16_f32 v156, v156, v157
	v_cvt_pk_bf16_f32 v157, v158, v159
	global_store_dwordx2 v[174:175], v[156:157], off offset:288
	s_and_saveexec_b64 s[42:43], s[6:7]
	s_cbranch_execz .LBB0_477
	v_lshl_add_u64 v[156:157], v[138:139], 2, s[28:29]
	s_waitcnt lgkmcnt(0)
	v_add_f32_e32 v132, v132, v146
	v_mov_b32_e32 v208, v132
	v_mov_b64_e32 v[176:177], v[156:157]
.LBB0_477:
	s_or_b64 exec, exec, s[42:43]
	s_waitcnt lgkmcnt(0)
	v_or_b32_e32 v146, 16, v138
	v_ashrrev_i32_e32 v147, 31, v146
	v_add_u32_e32 v132, 0xffff8010, v138
	v_lshlrev_b64 v[160:161], 12, v[146:147]
	v_lshlrev_b64 v[158:159], 12, v[132:133]
	v_lshl_add_u64 v[156:157], s[12:13], 0, v[160:161]
	v_lshl_add_u64 v[158:159], s[14:15], 0, v[158:159]
	v_cmp_gt_i32_e32 vcc, s66, v146
	v_lshlrev_b64 v[162:163], 11, v[146:147]
	v_lshl_add_u64 v[160:161], s[20:21], 0, v[160:161]
	v_cndmask_b32_e32 v157, v159, v157, vcc
	v_cndmask_b32_e32 v156, v158, v156, vcc
	v_lshl_add_u64 v[168:169], v[156:157], 0, v[144:145]
	global_load_dwordx4 v[156:159], v[168:169], off
	global_load_dwordx4 v[196:199], v[168:169], off offset:64
	global_load_dwordx4 v[200:203], v[168:169], off offset:512
	global_load_dwordx4 v[204:207], v[168:169], off offset:576
	v_lshl_add_u64 v[162:163], s[26:27], 0, v[162:163]
	v_lshl_add_u64 v[172:173], v[160:161], 0, v[144:145]
	v_lshl_add_u64 v[174:175], v[140:141], 1, v[162:163]
	s_waitcnt vmcnt(3) lgkmcnt(0)
	v_pk_fma_f32 v[158:159], v[110:111], 0.5, v[158:159] op_sel_hi:[1,0,1]
	v_pk_fma_f32 v[156:157], v[108:109], 0.5, v[156:157] op_sel_hi:[1,0,1]
	global_store_dwordx4 v[172:173], v[156:159], off sc1
	v_cvt_pk_bf16_f32 v160, v156, v157
	v_cvt_pk_bf16_f32 v161, v158, v159
	global_store_dwordx2 v[174:175], v[160:161], off
	v_mul_f32_e32 v132, v157, v157
	v_mul_f32_e32 v139, v159, v159
	v_fmac_f32_e32 v132, v156, v156
	v_fmac_f32_e32 v139, v158, v158
	v_add_f32_e32 v132, v132, v139
	s_waitcnt vmcnt(4) lgkmcnt(0)
	v_pk_fma_f32 v[198:199], v[106:107], 0.5, v[198:199] op_sel_hi:[1,0,1]
	v_pk_fma_f32 v[196:197], v[104:105], 0.5, v[196:197] op_sel_hi:[1,0,1]
	global_store_dwordx4 v[172:173], v[196:199], off offset:64 sc1
	v_cvt_pk_bf16_f32 v164, v196, v197
	v_cvt_pk_bf16_f32 v165, v198, v199
	global_store_dwordx2 v[174:175], v[164:165], off offset:32
	v_mul_f32_e32 v139, v197, v197
	v_mul_f32_e32 v156, v199, v199
	v_fmac_f32_e32 v139, v196, v196
	v_fmac_f32_e32 v156, v198, v198
	v_add_f32_e32 v139, v139, v156
	v_add_f32_e32 v132, v132, v139
	s_waitcnt vmcnt(5) lgkmcnt(0)
	v_pk_fma_f32 v[202:203], v[102:103], 0.5, v[202:203] op_sel_hi:[1,0,1]
	v_pk_fma_f32 v[200:201], v[100:101], 0.5, v[200:201] op_sel_hi:[1,0,1]
	global_store_dwordx4 v[172:173], v[200:203], off offset:512 sc1
	v_cvt_pk_bf16_f32 v170, v200, v201
	v_cvt_pk_bf16_f32 v171, v202, v203
	global_store_dwordx2 v[174:175], v[170:171], off offset:256
	v_mul_f32_e32 v139, v201, v201
	v_mul_f32_e32 v156, v203, v203
	v_fmac_f32_e32 v139, v200, v200
	v_fmac_f32_e32 v156, v202, v202
	v_add_f32_e32 v139, v139, v156
	v_add_f32_e32 v132, v132, v139
	s_waitcnt vmcnt(6) lgkmcnt(0)
	v_pk_fma_f32 v[158:159], v[98:99], 0.5, v[206:207] op_sel_hi:[1,0,1]
	v_pk_fma_f32 v[156:157], v[96:97], 0.5, v[204:205] op_sel_hi:[1,0,1]
	v_mul_f32_e32 v160, v159, v159
	v_mul_f32_e32 v139, v157, v157
	v_fmac_f32_e32 v139, v156, v156
	v_fmac_f32_e32 v160, v158, v158
	v_add_f32_e32 v139, v139, v160
	v_add_f32_e32 v132, v132, v139
	ds_bpermute_b32 v139, v143, v132
	global_store_dwordx4 v[172:173], v[156:159], off offset:576 sc1
	s_waitcnt lgkmcnt(0)
	v_add_f32_e32 v132, v132, v139
	ds_bpermute_b32 v139, v155, v132
	v_cvt_pk_bf16_f32 v156, v156, v157
	v_cvt_pk_bf16_f32 v157, v158, v159
	global_store_dwordx2 v[174:175], v[156:157], off offset:288
	s_and_saveexec_b64 s[42:43], s[6:7]
	s_cbranch_execz .LBB0_479
	v_lshl_add_u64 v[146:147], v[146:147], 2, s[28:29]
	s_waitcnt lgkmcnt(0)
	v_add_f32_e32 v132, v132, v139
	v_mov_b32_e32 v209, v132
.LBB0_479:
	s_or_b64 exec, exec, s[42:43]
	v_or_b32_e32 v146, 32, v138
	v_ashrrev_i32_e32 v147, 31, v146
	v_add_u32_e32 v132, 0xffff8020, v138
	v_lshlrev_b64 v[160:161], 12, v[146:147]
	v_lshlrev_b64 v[158:159], 12, v[132:133]
	v_lshl_add_u64 v[156:157], s[12:13], 0, v[160:161]
	v_lshl_add_u64 v[158:159], s[14:15], 0, v[158:159]
	v_cmp_gt_i32_e32 vcc, s66, v146
	v_lshlrev_b64 v[162:163], 11, v[146:147]
	v_lshl_add_u64 v[160:161], s[20:21], 0, v[160:161]
	v_cndmask_b32_e32 v157, v159, v157, vcc
	v_cndmask_b32_e32 v156, v158, v156, vcc
	v_lshl_add_u64 v[168:169], v[156:157], 0, v[144:145]
	global_load_dwordx4 v[156:159], v[168:169], off
	global_load_dwordx4 v[184:187], v[168:169], off offset:64
	global_load_dwordx4 v[188:191], v[168:169], off offset:512
	global_load_dwordx4 v[192:195], v[168:169], off offset:576
	v_lshl_add_u64 v[162:163], s[26:27], 0, v[162:163]
	v_lshl_add_u64 v[172:173], v[160:161], 0, v[144:145]
	v_lshl_add_u64 v[174:175], v[140:141], 1, v[162:163]
	s_waitcnt vmcnt(3) lgkmcnt(0)
	v_pk_fma_f32 v[158:159], v[94:95], 0.5, v[158:159] op_sel_hi:[1,0,1]
	v_pk_fma_f32 v[156:157], v[92:93], 0.5, v[156:157] op_sel_hi:[1,0,1]
	global_store_dwordx4 v[172:173], v[156:159], off sc1
	v_cvt_pk_bf16_f32 v160, v156, v157
	v_cvt_pk_bf16_f32 v161, v158, v159
	global_store_dwordx2 v[174:175], v[160:161], off
	v_mul_f32_e32 v132, v157, v157
	v_mul_f32_e32 v139, v159, v159
	v_fmac_f32_e32 v132, v156, v156
	v_fmac_f32_e32 v139, v158, v158
	v_add_f32_e32 v132, v132, v139
	s_waitcnt vmcnt(4) lgkmcnt(0)
	v_pk_fma_f32 v[186:187], v[90:91], 0.5, v[186:187] op_sel_hi:[1,0,1]
	v_pk_fma_f32 v[184:185], v[88:89], 0.5, v[184:185] op_sel_hi:[1,0,1]
	global_store_dwordx4 v[172:173], v[184:187], off offset:64 sc1
	v_cvt_pk_bf16_f32 v164, v184, v185
	v_cvt_pk_bf16_f32 v165, v186, v187
	global_store_dwordx2 v[174:175], v[164:165], off offset:32
	v_mul_f32_e32 v139, v185, v185
	v_mul_f32_e32 v156, v187, v187
	v_fmac_f32_e32 v139, v184, v184
	v_fmac_f32_e32 v156, v186, v186
	v_add_f32_e32 v139, v139, v156
	v_add_f32_e32 v132, v132, v139
	s_waitcnt vmcnt(5) lgkmcnt(0)
	v_pk_fma_f32 v[190:191], v[86:87], 0.5, v[190:191] op_sel_hi:[1,0,1]
	v_pk_fma_f32 v[188:189], v[84:85], 0.5, v[188:189] op_sel_hi:[1,0,1]
	global_store_dwordx4 v[172:173], v[188:191], off offset:512 sc1
	v_cvt_pk_bf16_f32 v170, v188, v189
	v_cvt_pk_bf16_f32 v171, v190, v191
	global_store_dwordx2 v[174:175], v[170:171], off offset:256
	v_mul_f32_e32 v139, v189, v189
	v_mul_f32_e32 v156, v191, v191
	v_fmac_f32_e32 v139, v188, v188
	v_fmac_f32_e32 v156, v190, v190
	v_add_f32_e32 v139, v139, v156
	v_add_f32_e32 v132, v132, v139
	s_waitcnt vmcnt(6) lgkmcnt(0)
	v_pk_fma_f32 v[158:159], v[82:83], 0.5, v[194:195] op_sel_hi:[1,0,1]
	v_pk_fma_f32 v[156:157], v[80:81], 0.5, v[192:193] op_sel_hi:[1,0,1]
	v_mul_f32_e32 v160, v159, v159
	v_mul_f32_e32 v139, v157, v157
	v_fmac_f32_e32 v139, v156, v156
	v_fmac_f32_e32 v160, v158, v158
	v_add_f32_e32 v139, v139, v160
	v_add_f32_e32 v132, v132, v139
	ds_bpermute_b32 v139, v143, v132
	global_store_dwordx4 v[172:173], v[156:159], off offset:576 sc1
	s_waitcnt lgkmcnt(0)
	v_add_f32_e32 v132, v132, v139
	ds_bpermute_b32 v139, v155, v132
	v_cvt_pk_bf16_f32 v156, v156, v157
	v_cvt_pk_bf16_f32 v157, v158, v159
	global_store_dwordx2 v[174:175], v[156:157], off offset:288
	s_and_saveexec_b64 s[42:43], s[6:7]
	s_cbranch_execz .LBB0_481
	v_lshl_add_u64 v[146:147], v[146:147], 2, s[28:29]
	s_waitcnt lgkmcnt(0)
	v_add_f32_e32 v132, v132, v139
	v_mov_b32_e32 v210, v132
.LBB0_481:
	s_or_b64 exec, exec, s[42:43]
	v_or_b32_e32 v146, 48, v138
	v_ashrrev_i32_e32 v147, 31, v146
	v_add_u32_e32 v132, 0xffff8030, v138
	v_lshlrev_b64 v[160:161], 12, v[146:147]
	v_lshlrev_b64 v[158:159], 12, v[132:133]
	v_lshl_add_u64 v[156:157], s[12:13], 0, v[160:161]
	v_lshl_add_u64 v[158:159], s[14:15], 0, v[158:159]
	v_cmp_gt_i32_e32 vcc, s66, v146
	v_lshlrev_b64 v[162:163], 11, v[146:147]
	v_lshl_add_u64 v[160:161], s[20:21], 0, v[160:161]
	v_cndmask_b32_e32 v157, v159, v157, vcc
	v_cndmask_b32_e32 v156, v158, v156, vcc
	v_lshl_add_u64 v[168:169], v[156:157], 0, v[144:145]
	global_load_dwordx4 v[156:159], v[168:169], off
	global_load_dwordx4 v[196:199], v[168:169], off offset:64
	global_load_dwordx4 v[200:203], v[168:169], off offset:512
	global_load_dwordx4 v[204:207], v[168:169], off offset:576
	v_lshl_add_u64 v[162:163], s[26:27], 0, v[162:163]
	v_lshl_add_u64 v[172:173], v[160:161], 0, v[144:145]
	v_lshl_add_u64 v[174:175], v[140:141], 1, v[162:163]
	s_waitcnt vmcnt(3) lgkmcnt(0)
	v_pk_fma_f32 v[158:159], v[78:79], 0.5, v[158:159] op_sel_hi:[1,0,1]
	v_pk_fma_f32 v[156:157], v[76:77], 0.5, v[156:157] op_sel_hi:[1,0,1]
	global_store_dwordx4 v[172:173], v[156:159], off sc1
	v_cvt_pk_bf16_f32 v160, v156, v157
	v_cvt_pk_bf16_f32 v161, v158, v159
	global_store_dwordx2 v[174:175], v[160:161], off
	v_mul_f32_e32 v132, v157, v157
	v_mul_f32_e32 v139, v159, v159
	v_fmac_f32_e32 v132, v156, v156
	v_fmac_f32_e32 v139, v158, v158
	v_add_f32_e32 v132, v132, v139
	s_waitcnt vmcnt(4) lgkmcnt(0)
	v_pk_fma_f32 v[198:199], v[74:75], 0.5, v[198:199] op_sel_hi:[1,0,1]
	v_pk_fma_f32 v[196:197], v[72:73], 0.5, v[196:197] op_sel_hi:[1,0,1]
	global_store_dwordx4 v[172:173], v[196:199], off offset:64 sc1
	v_cvt_pk_bf16_f32 v164, v196, v197
	v_cvt_pk_bf16_f32 v165, v198, v199
	global_store_dwordx2 v[174:175], v[164:165], off offset:32
	v_mul_f32_e32 v139, v197, v197
	v_mul_f32_e32 v156, v199, v199
	v_fmac_f32_e32 v139, v196, v196
	v_fmac_f32_e32 v156, v198, v198
	v_add_f32_e32 v139, v139, v156
	v_add_f32_e32 v132, v132, v139
	s_waitcnt vmcnt(5) lgkmcnt(0)
	v_pk_fma_f32 v[202:203], v[70:71], 0.5, v[202:203] op_sel_hi:[1,0,1]
	v_pk_fma_f32 v[200:201], v[68:69], 0.5, v[200:201] op_sel_hi:[1,0,1]
	global_store_dwordx4 v[172:173], v[200:203], off offset:512 sc1
	v_cvt_pk_bf16_f32 v170, v200, v201
	v_cvt_pk_bf16_f32 v171, v202, v203
	global_store_dwordx2 v[174:175], v[170:171], off offset:256
	v_mul_f32_e32 v139, v201, v201
	v_mul_f32_e32 v156, v203, v203
	v_fmac_f32_e32 v139, v200, v200
	v_fmac_f32_e32 v156, v202, v202
	v_add_f32_e32 v139, v139, v156
	v_add_f32_e32 v132, v132, v139
	s_waitcnt vmcnt(6) lgkmcnt(0)
	v_pk_fma_f32 v[158:159], v[66:67], 0.5, v[206:207] op_sel_hi:[1,0,1]
	v_pk_fma_f32 v[156:157], v[64:65], 0.5, v[204:205] op_sel_hi:[1,0,1]
	v_mul_f32_e32 v160, v159, v159
	v_mul_f32_e32 v139, v157, v157
	v_fmac_f32_e32 v139, v156, v156
	v_fmac_f32_e32 v160, v158, v158
	v_add_f32_e32 v139, v139, v160
	v_add_f32_e32 v132, v132, v139
	ds_bpermute_b32 v139, v143, v132
	global_store_dwordx4 v[172:173], v[156:159], off offset:576 sc1
	s_waitcnt lgkmcnt(0)
	v_add_f32_e32 v132, v132, v139
	ds_bpermute_b32 v139, v155, v132
	v_cvt_pk_bf16_f32 v156, v156, v157
	v_cvt_pk_bf16_f32 v157, v158, v159
	global_store_dwordx2 v[174:175], v[156:157], off offset:288
	s_and_saveexec_b64 s[42:43], s[6:7]
	s_cbranch_execz .LBB0_483
	v_lshl_add_u64 v[146:147], v[146:147], 2, s[28:29]
	s_waitcnt lgkmcnt(0)
	v_add_f32_e32 v132, v132, v139
	v_mov_b32_e32 v211, v132
.LBB0_483:
	s_or_b64 exec, exec, s[42:43]
	v_add_u32_e32 v146, 0x80, v138
	v_ashrrev_i32_e32 v147, 31, v146
	v_add_u32_e32 v132, 0xffff8080, v138
	v_lshlrev_b64 v[160:161], 12, v[146:147]
	v_lshlrev_b64 v[158:159], 12, v[132:133]
	v_lshl_add_u64 v[156:157], s[12:13], 0, v[160:161]
	v_lshl_add_u64 v[158:159], s[14:15], 0, v[158:159]
	v_cmp_gt_i32_e32 vcc, s86, v138
	v_lshlrev_b64 v[162:163], 11, v[146:147]
	v_lshl_add_u64 v[160:161], s[20:21], 0, v[160:161]
	v_cndmask_b32_e32 v157, v159, v157, vcc
	v_cndmask_b32_e32 v156, v158, v156, vcc
	v_lshl_add_u64 v[168:169], v[156:157], 0, v[144:145]
	global_load_dwordx4 v[156:159], v[168:169], off
	global_load_dwordx4 v[184:187], v[168:169], off offset:64
	global_load_dwordx4 v[188:191], v[168:169], off offset:512
	global_load_dwordx4 v[192:195], v[168:169], off offset:576
	v_lshl_add_u64 v[162:163], s[26:27], 0, v[162:163]
	v_lshl_add_u64 v[172:173], v[160:161], 0, v[144:145]
	v_lshl_add_u64 v[174:175], v[140:141], 1, v[162:163]
	s_waitcnt vmcnt(3) lgkmcnt(0)
	v_pk_fma_f32 v[158:159], v[62:63], 0.5, v[158:159] op_sel_hi:[1,0,1]
	v_pk_fma_f32 v[156:157], v[60:61], 0.5, v[156:157] op_sel_hi:[1,0,1]
	global_store_dwordx4 v[172:173], v[156:159], off sc1
	v_cvt_pk_bf16_f32 v160, v156, v157
	v_cvt_pk_bf16_f32 v161, v158, v159
	global_store_dwordx2 v[174:175], v[160:161], off
	v_mul_f32_e32 v132, v157, v157
	v_mul_f32_e32 v139, v159, v159
	v_fmac_f32_e32 v132, v156, v156
	v_fmac_f32_e32 v139, v158, v158
	v_add_f32_e32 v132, v132, v139
	s_waitcnt vmcnt(4) lgkmcnt(0)
	v_pk_fma_f32 v[186:187], v[58:59], 0.5, v[186:187] op_sel_hi:[1,0,1]
	v_pk_fma_f32 v[184:185], v[56:57], 0.5, v[184:185] op_sel_hi:[1,0,1]
	global_store_dwordx4 v[172:173], v[184:187], off offset:64 sc1
	v_cvt_pk_bf16_f32 v164, v184, v185
	v_cvt_pk_bf16_f32 v165, v186, v187
	global_store_dwordx2 v[174:175], v[164:165], off offset:32
	v_mul_f32_e32 v139, v185, v185
	v_mul_f32_e32 v156, v187, v187
	v_fmac_f32_e32 v139, v184, v184
	v_fmac_f32_e32 v156, v186, v186
	v_add_f32_e32 v139, v139, v156
	v_add_f32_e32 v132, v132, v139
	s_waitcnt vmcnt(5) lgkmcnt(0)
	v_pk_fma_f32 v[190:191], v[54:55], 0.5, v[190:191] op_sel_hi:[1,0,1]
	v_pk_fma_f32 v[188:189], v[52:53], 0.5, v[188:189] op_sel_hi:[1,0,1]
	global_store_dwordx4 v[172:173], v[188:191], off offset:512 sc1
	v_cvt_pk_bf16_f32 v170, v188, v189
	v_cvt_pk_bf16_f32 v171, v190, v191
	global_store_dwordx2 v[174:175], v[170:171], off offset:256
	v_mul_f32_e32 v139, v189, v189
	v_mul_f32_e32 v156, v191, v191
	v_fmac_f32_e32 v139, v188, v188
	v_fmac_f32_e32 v156, v190, v190
	v_add_f32_e32 v139, v139, v156
	v_add_f32_e32 v132, v132, v139
	s_waitcnt vmcnt(6) lgkmcnt(0)
	v_pk_fma_f32 v[158:159], v[50:51], 0.5, v[194:195] op_sel_hi:[1,0,1]
	v_pk_fma_f32 v[156:157], v[48:49], 0.5, v[192:193] op_sel_hi:[1,0,1]
	v_mul_f32_e32 v160, v159, v159
	v_mul_f32_e32 v139, v157, v157
	v_fmac_f32_e32 v139, v156, v156
	v_fmac_f32_e32 v160, v158, v158
	v_add_f32_e32 v139, v139, v160
	v_add_f32_e32 v132, v132, v139
	ds_bpermute_b32 v139, v143, v132
	global_store_dwordx4 v[172:173], v[156:159], off offset:576 sc1
	s_waitcnt lgkmcnt(0)
	v_add_f32_e32 v132, v132, v139
	ds_bpermute_b32 v139, v155, v132
	v_cvt_pk_bf16_f32 v156, v156, v157
	v_cvt_pk_bf16_f32 v157, v158, v159
	global_store_dwordx2 v[174:175], v[156:157], off offset:288
	s_and_saveexec_b64 s[42:43], s[6:7]
	s_cbranch_execz .LBB0_485
	v_lshl_add_u64 v[146:147], v[146:147], 2, s[28:29]
	s_waitcnt lgkmcnt(0)
	v_add_f32_e32 v132, v132, v139
	v_mov_b32_e32 v212, v132
.LBB0_485:
	s_or_b64 exec, exec, s[42:43]
	v_add_u32_e32 v146, 0x90, v138
	v_ashrrev_i32_e32 v147, 31, v146
	v_add_u32_e32 v132, 0xffff8090, v138
	v_lshlrev_b64 v[160:161], 12, v[146:147]
	v_lshlrev_b64 v[158:159], 12, v[132:133]
	v_lshl_add_u64 v[156:157], s[12:13], 0, v[160:161]
	v_lshl_add_u64 v[158:159], s[14:15], 0, v[158:159]
	v_cmp_gt_i32_e32 vcc, s87, v138
	v_lshlrev_b64 v[162:163], 11, v[146:147]
	v_lshl_add_u64 v[160:161], s[20:21], 0, v[160:161]
	v_cndmask_b32_e32 v157, v159, v157, vcc
	v_cndmask_b32_e32 v156, v158, v156, vcc
	v_lshl_add_u64 v[168:169], v[156:157], 0, v[144:145]
	global_load_dwordx4 v[156:159], v[168:169], off
	global_load_dwordx4 v[196:199], v[168:169], off offset:64
	global_load_dwordx4 v[200:203], v[168:169], off offset:512
	global_load_dwordx4 v[204:207], v[168:169], off offset:576
	v_lshl_add_u64 v[162:163], s[26:27], 0, v[162:163]
	v_lshl_add_u64 v[172:173], v[160:161], 0, v[144:145]
	v_lshl_add_u64 v[174:175], v[140:141], 1, v[162:163]
	s_waitcnt vmcnt(3) lgkmcnt(0)
	v_pk_fma_f32 v[158:159], v[46:47], 0.5, v[158:159] op_sel_hi:[1,0,1]
	v_pk_fma_f32 v[156:157], v[44:45], 0.5, v[156:157] op_sel_hi:[1,0,1]
	global_store_dwordx4 v[172:173], v[156:159], off sc1
	v_cvt_pk_bf16_f32 v160, v156, v157
	v_cvt_pk_bf16_f32 v161, v158, v159
	global_store_dwordx2 v[174:175], v[160:161], off
	v_mul_f32_e32 v132, v157, v157
	v_mul_f32_e32 v139, v159, v159
	v_fmac_f32_e32 v132, v156, v156
	v_fmac_f32_e32 v139, v158, v158
	v_add_f32_e32 v132, v132, v139
	s_waitcnt vmcnt(4) lgkmcnt(0)
	v_pk_fma_f32 v[198:199], v[42:43], 0.5, v[198:199] op_sel_hi:[1,0,1]
	v_pk_fma_f32 v[196:197], v[40:41], 0.5, v[196:197] op_sel_hi:[1,0,1]
	global_store_dwordx4 v[172:173], v[196:199], off offset:64 sc1
	v_cvt_pk_bf16_f32 v164, v196, v197
	v_cvt_pk_bf16_f32 v165, v198, v199
	global_store_dwordx2 v[174:175], v[164:165], off offset:32
	v_mul_f32_e32 v139, v197, v197
	v_mul_f32_e32 v156, v199, v199
	v_fmac_f32_e32 v139, v196, v196
	v_fmac_f32_e32 v156, v198, v198
	v_add_f32_e32 v139, v139, v156
	v_add_f32_e32 v132, v132, v139
	s_waitcnt vmcnt(5) lgkmcnt(0)
	v_pk_fma_f32 v[202:203], v[38:39], 0.5, v[202:203] op_sel_hi:[1,0,1]
	v_pk_fma_f32 v[200:201], v[36:37], 0.5, v[200:201] op_sel_hi:[1,0,1]
	global_store_dwordx4 v[172:173], v[200:203], off offset:512 sc1
	v_cvt_pk_bf16_f32 v170, v200, v201
	v_cvt_pk_bf16_f32 v171, v202, v203
	global_store_dwordx2 v[174:175], v[170:171], off offset:256
	v_mul_f32_e32 v139, v201, v201
	v_mul_f32_e32 v156, v203, v203
	v_fmac_f32_e32 v139, v200, v200
	v_fmac_f32_e32 v156, v202, v202
	v_add_f32_e32 v139, v139, v156
	v_add_f32_e32 v132, v132, v139
	s_waitcnt vmcnt(6) lgkmcnt(0)
	v_pk_fma_f32 v[158:159], v[34:35], 0.5, v[206:207] op_sel_hi:[1,0,1]
	v_pk_fma_f32 v[156:157], v[32:33], 0.5, v[204:205] op_sel_hi:[1,0,1]
	v_mul_f32_e32 v160, v159, v159
	v_mul_f32_e32 v139, v157, v157
	v_fmac_f32_e32 v139, v156, v156
	v_fmac_f32_e32 v160, v158, v158
	v_add_f32_e32 v139, v139, v160
	v_add_f32_e32 v132, v132, v139
	ds_bpermute_b32 v139, v143, v132
	global_store_dwordx4 v[172:173], v[156:159], off offset:576 sc1
	s_waitcnt lgkmcnt(0)
	v_add_f32_e32 v132, v132, v139
	ds_bpermute_b32 v139, v155, v132
	v_cvt_pk_bf16_f32 v156, v156, v157
	v_cvt_pk_bf16_f32 v157, v158, v159
	global_store_dwordx2 v[174:175], v[156:157], off offset:288
	s_and_saveexec_b64 s[42:43], s[6:7]
	s_cbranch_execz .LBB0_487
	v_lshl_add_u64 v[146:147], v[146:147], 2, s[28:29]
	s_waitcnt lgkmcnt(0)
	v_add_f32_e32 v132, v132, v139
	v_mov_b32_e32 v213, v132
.LBB0_487:
	s_or_b64 exec, exec, s[42:43]
	v_add_u32_e32 v146, 0xa0, v138
	v_ashrrev_i32_e32 v147, 31, v146
	v_add_u32_e32 v132, 0xffff80a0, v138
	v_lshlrev_b64 v[160:161], 12, v[146:147]
	v_lshlrev_b64 v[158:159], 12, v[132:133]
	v_lshl_add_u64 v[156:157], s[12:13], 0, v[160:161]
	v_lshl_add_u64 v[158:159], s[14:15], 0, v[158:159]
	v_cmp_gt_i32_e32 vcc, s88, v138
	v_lshlrev_b64 v[162:163], 11, v[146:147]
	v_lshl_add_u64 v[160:161], s[20:21], 0, v[160:161]
	v_cndmask_b32_e32 v157, v159, v157, vcc
	v_cndmask_b32_e32 v156, v158, v156, vcc
	v_lshl_add_u64 v[168:169], v[156:157], 0, v[144:145]
	global_load_dwordx4 v[156:159], v[168:169], off
	global_load_dwordx4 v[184:187], v[168:169], off offset:64
	global_load_dwordx4 v[188:191], v[168:169], off offset:512
	global_load_dwordx4 v[192:195], v[168:169], off offset:576
	v_lshl_add_u64 v[162:163], s[26:27], 0, v[162:163]
	v_lshl_add_u64 v[172:173], v[160:161], 0, v[144:145]
	v_lshl_add_u64 v[174:175], v[140:141], 1, v[162:163]
	s_waitcnt vmcnt(3) lgkmcnt(0)
	v_pk_fma_f32 v[158:159], v[30:31], 0.5, v[158:159] op_sel_hi:[1,0,1]
	v_pk_fma_f32 v[156:157], v[28:29], 0.5, v[156:157] op_sel_hi:[1,0,1]
	global_store_dwordx4 v[172:173], v[156:159], off sc1
	v_cvt_pk_bf16_f32 v160, v156, v157
	v_cvt_pk_bf16_f32 v161, v158, v159
	global_store_dwordx2 v[174:175], v[160:161], off
	v_mul_f32_e32 v132, v157, v157
	v_mul_f32_e32 v139, v159, v159
	v_fmac_f32_e32 v132, v156, v156
	v_fmac_f32_e32 v139, v158, v158
	v_add_f32_e32 v132, v132, v139
	s_waitcnt vmcnt(4) lgkmcnt(0)
	v_pk_fma_f32 v[186:187], v[26:27], 0.5, v[186:187] op_sel_hi:[1,0,1]
	v_pk_fma_f32 v[184:185], v[24:25], 0.5, v[184:185] op_sel_hi:[1,0,1]
	global_store_dwordx4 v[172:173], v[184:187], off offset:64 sc1
	v_cvt_pk_bf16_f32 v164, v184, v185
	v_cvt_pk_bf16_f32 v165, v186, v187
	global_store_dwordx2 v[174:175], v[164:165], off offset:32
	v_mul_f32_e32 v139, v185, v185
	v_mul_f32_e32 v156, v187, v187
	v_fmac_f32_e32 v139, v184, v184
	v_fmac_f32_e32 v156, v186, v186
	v_add_f32_e32 v139, v139, v156
	v_add_f32_e32 v132, v132, v139
	s_waitcnt vmcnt(5) lgkmcnt(0)
	v_pk_fma_f32 v[190:191], v[22:23], 0.5, v[190:191] op_sel_hi:[1,0,1]
	v_pk_fma_f32 v[188:189], v[20:21], 0.5, v[188:189] op_sel_hi:[1,0,1]
	global_store_dwordx4 v[172:173], v[188:191], off offset:512 sc1
	v_cvt_pk_bf16_f32 v170, v188, v189
	v_cvt_pk_bf16_f32 v171, v190, v191
	global_store_dwordx2 v[174:175], v[170:171], off offset:256
	v_mul_f32_e32 v139, v189, v189
	v_mul_f32_e32 v156, v191, v191
	v_fmac_f32_e32 v139, v188, v188
	v_fmac_f32_e32 v156, v190, v190
	v_add_f32_e32 v139, v139, v156
	v_add_f32_e32 v132, v132, v139
	s_waitcnt vmcnt(6) lgkmcnt(0)
	v_pk_fma_f32 v[158:159], v[18:19], 0.5, v[194:195] op_sel_hi:[1,0,1]
	v_pk_fma_f32 v[156:157], v[16:17], 0.5, v[192:193] op_sel_hi:[1,0,1]
	v_mul_f32_e32 v160, v159, v159
	v_mul_f32_e32 v139, v157, v157
	v_fmac_f32_e32 v139, v156, v156
	v_fmac_f32_e32 v160, v158, v158
	v_add_f32_e32 v139, v139, v160
	v_add_f32_e32 v132, v132, v139
	ds_bpermute_b32 v139, v143, v132
	global_store_dwordx4 v[172:173], v[156:159], off offset:576 sc1
	s_waitcnt lgkmcnt(0)
	v_add_f32_e32 v132, v132, v139
	ds_bpermute_b32 v139, v155, v132
	v_cvt_pk_bf16_f32 v156, v156, v157
	v_cvt_pk_bf16_f32 v157, v158, v159
	global_store_dwordx2 v[174:175], v[156:157], off offset:288
	s_and_saveexec_b64 s[42:43], s[6:7]
	s_cbranch_execz .LBB0_489
	v_lshl_add_u64 v[146:147], v[146:147], 2, s[28:29]
	s_waitcnt lgkmcnt(0)
	v_add_f32_e32 v132, v132, v139
	v_mov_b32_e32 v214, v132
.LBB0_489:
	s_or_b64 exec, exec, s[42:43]
	v_add_u32_e32 v146, 0xb0, v138
	v_ashrrev_i32_e32 v147, 31, v146
	v_add_u32_e32 v132, 0xffff80b0, v138
	v_lshlrev_b64 v[160:161], 12, v[146:147]
	v_lshlrev_b64 v[158:159], 12, v[132:133]
	v_lshl_add_u64 v[156:157], s[12:13], 0, v[160:161]
	v_lshl_add_u64 v[158:159], s[14:15], 0, v[158:159]
	v_cmp_gt_i32_e32 vcc, s89, v138
	v_lshlrev_b64 v[162:163], 11, v[146:147]
	v_lshl_add_u64 v[160:161], s[20:21], 0, v[160:161]
	v_cndmask_b32_e32 v157, v159, v157, vcc
	v_cndmask_b32_e32 v156, v158, v156, vcc
	v_lshl_add_u64 v[168:169], v[156:157], 0, v[144:145]
	global_load_dwordx4 v[156:159], v[168:169], off
	global_load_dwordx4 v[196:199], v[168:169], off offset:64
	global_load_dwordx4 v[200:203], v[168:169], off offset:512
	global_load_dwordx4 v[204:207], v[168:169], off offset:576
	v_lshl_add_u64 v[162:163], s[26:27], 0, v[162:163]
	v_lshl_add_u64 v[144:145], v[160:161], 0, v[144:145]
	v_lshl_add_u64 v[172:173], v[140:141], 1, v[162:163]
	s_waitcnt vmcnt(3) lgkmcnt(0)
	v_pk_fma_f32 v[158:159], v[14:15], 0.5, v[158:159] op_sel_hi:[1,0,1]
	v_pk_fma_f32 v[156:157], v[12:13], 0.5, v[156:157] op_sel_hi:[1,0,1]
	global_store_dwordx4 v[144:145], v[156:159], off sc1
	v_cvt_pk_bf16_f32 v160, v156, v157
	v_cvt_pk_bf16_f32 v161, v158, v159
	global_store_dwordx2 v[172:173], v[160:161], off
	v_mul_f32_e32 v132, v157, v157
	v_mul_f32_e32 v139, v159, v159
	v_fmac_f32_e32 v132, v156, v156
	v_fmac_f32_e32 v139, v158, v158
	v_add_f32_e32 v132, v132, v139
	s_waitcnt vmcnt(4) lgkmcnt(0)
	v_pk_fma_f32 v[198:199], v[10:11], 0.5, v[198:199] op_sel_hi:[1,0,1]
	v_pk_fma_f32 v[196:197], v[8:9], 0.5, v[196:197] op_sel_hi:[1,0,1]
	global_store_dwordx4 v[144:145], v[196:199], off offset:64 sc1
	v_cvt_pk_bf16_f32 v164, v196, v197
	v_cvt_pk_bf16_f32 v165, v198, v199
	global_store_dwordx2 v[172:173], v[164:165], off offset:32
	v_mul_f32_e32 v139, v197, v197
	v_mul_f32_e32 v156, v199, v199
	v_fmac_f32_e32 v139, v196, v196
	v_fmac_f32_e32 v156, v198, v198
	v_add_f32_e32 v139, v139, v156
	v_add_f32_e32 v132, v132, v139
	s_waitcnt vmcnt(5) lgkmcnt(0)
	v_pk_fma_f32 v[202:203], v[6:7], 0.5, v[202:203] op_sel_hi:[1,0,1]
	v_pk_fma_f32 v[200:201], v[4:5], 0.5, v[200:201] op_sel_hi:[1,0,1]
	global_store_dwordx4 v[144:145], v[200:203], off offset:512 sc1
	v_cvt_pk_bf16_f32 v170, v200, v201
	v_cvt_pk_bf16_f32 v171, v202, v203
	global_store_dwordx2 v[172:173], v[170:171], off offset:256
	v_mul_f32_e32 v139, v201, v201
	v_mul_f32_e32 v156, v203, v203
	v_fmac_f32_e32 v139, v200, v200
	v_fmac_f32_e32 v156, v202, v202
	v_add_f32_e32 v139, v139, v156
	v_add_f32_e32 v132, v132, v139
	s_waitcnt vmcnt(6) lgkmcnt(0)
	v_pk_fma_f32 v[158:159], v[2:3], 0.5, v[206:207] op_sel_hi:[1,0,1]
	v_pk_fma_f32 v[156:157], v[0:1], 0.5, v[204:205] op_sel_hi:[1,0,1]
	v_mul_f32_e32 v160, v159, v159
	v_mul_f32_e32 v139, v157, v157
	v_fmac_f32_e32 v139, v156, v156
	v_fmac_f32_e32 v160, v158, v158
	v_add_f32_e32 v139, v139, v160
	v_add_f32_e32 v132, v132, v139
	ds_bpermute_b32 v139, v143, v132
	global_store_dwordx4 v[144:145], v[156:159], off offset:576 sc1
	v_cvt_pk_bf16_f32 v144, v156, v157
	v_cvt_pk_bf16_f32 v145, v158, v159
	global_store_dwordx2 v[172:173], v[144:145], off offset:288
	s_waitcnt lgkmcnt(0)
	v_add_f32_e32 v132, v132, v139
	ds_bpermute_b32 v139, v155, v132
	s_and_saveexec_b64 s[42:43], s[6:7]
	s_cbranch_execz .LBB0_491
	v_lshl_add_u64 v[144:145], v[146:147], 2, s[28:29]
	s_waitcnt lgkmcnt(0)
	v_add_f32_e32 v132, v132, v139
	v_mov_b32_e32 v215, v132

.LBB0_1610:
	v_ashrrev_i32_e32 v137, 31, v136
	v_lshlrev_b64 v[140:141], 12, v[136:137]
	v_lshl_add_u64 v[140:141], s[16:17], 0, v[140:141]
	v_lshl_add_u64 v[166:167], v[138:139], 2, v[140:141]
	global_load_dwordx4 v[150:153], v[166:167], off
	global_load_dwordx4 v[184:187], v[166:167], off offset:64
	global_load_dwordx4 v[188:191], v[166:167], off offset:512
	global_load_dwordx4 v[192:195], v[166:167], off offset:576
	v_lshlrev_b64 v[140:141], 11, v[136:137]
	v_lshl_add_u64 v[140:141], s[22:23], 0, v[140:141]
	v_lshl_add_u64 v[168:169], v[138:139], 1, v[140:141]
	s_waitcnt vmcnt(3) lgkmcnt(0)
	v_pk_add_f32 v[152:153], v[126:127], v[152:153]
	v_pk_add_f32 v[150:151], v[124:125], v[150:151]
	global_store_dwordx4 v[166:167], v[150:153], off sc1
	v_cvt_pk_bf16_f32 v140, v150, v151
	v_cvt_pk_bf16_f32 v141, v152, v153
	global_store_dwordx2 v[168:169], v[140:141], off
	s_waitcnt vmcnt(4) lgkmcnt(0)
	v_pk_add_f32 v[186:187], v[122:123], v[186:187]
	v_pk_add_f32 v[184:185], v[120:121], v[184:185]
	global_store_dwordx4 v[166:167], v[184:187], off offset:64 sc1
	v_cvt_pk_bf16_f32 v140, v184, v185
	v_cvt_pk_bf16_f32 v141, v186, v187
	global_store_dwordx2 v[168:169], v[140:141], off offset:32
	s_waitcnt vmcnt(5) lgkmcnt(0)
	v_pk_add_f32 v[190:191], v[110:111], v[190:191]
	v_pk_add_f32 v[188:189], v[108:109], v[188:189]
	global_store_dwordx4 v[166:167], v[188:191], off offset:512 sc1
	v_cvt_pk_bf16_f32 v140, v188, v189
	v_cvt_pk_bf16_f32 v141, v190, v191
	global_store_dwordx2 v[168:169], v[140:141], off offset:256
	v_and_b32_e32 v141, 64, v148
	v_xor_b32_e32 v140, 16, v148
	v_add_u32_e32 v141, 64, v141
	v_cmp_lt_i32_e32 vcc, v140, v141
	s_nop 1
	v_cndmask_b32_e32 v140, v148, v140, vcc
	v_lshlrev_b32_e32 v149, 2, v140
	v_mul_f32_e32 v140, v151, v151
	v_mul_f32_e32 v151, v153, v153
	v_fmac_f32_e32 v140, v150, v150
	v_fmac_f32_e32 v151, v152, v152
	v_add_f32_e32 v140, v140, v151
	v_mul_f32_e32 v150, v185, v185
	v_mul_f32_e32 v151, v187, v187
	v_fmac_f32_e32 v150, v184, v184
	v_fmac_f32_e32 v151, v186, v186
	v_add_f32_e32 v150, v150, v151
	v_add_f32_e32 v140, v140, v150
	v_mul_f32_e32 v150, v189, v189
	v_mul_f32_e32 v151, v191, v191
	v_fmac_f32_e32 v150, v188, v188
	v_fmac_f32_e32 v151, v190, v190
	v_add_f32_e32 v150, v150, v151
	v_add_f32_e32 v140, v140, v150
	s_waitcnt vmcnt(6) lgkmcnt(0)
	v_pk_add_f32 v[154:155], v[102:103], v[194:195]
	v_pk_add_f32 v[152:153], v[100:101], v[192:193]
	v_mul_f32_e32 v151, v155, v155
	v_mul_f32_e32 v150, v153, v153
	v_fmac_f32_e32 v150, v152, v152
	v_fmac_f32_e32 v151, v154, v154
	v_add_f32_e32 v150, v150, v151
	v_add_f32_e32 v140, v140, v150
	ds_bpermute_b32 v150, v149, v140
	v_xor_b32_e32 v151, 32, v148
	v_cmp_lt_i32_e32 vcc, v151, v141
	global_store_dwordx4 v[166:167], v[152:155], off offset:576 sc1
	s_waitcnt lgkmcnt(0)
	v_add_f32_e32 v140, v140, v150
	v_cndmask_b32_e32 v141, v148, v151, vcc
	v_lshlrev_b32_e32 v150, 2, v141
	ds_bpermute_b32 v141, v150, v140
	v_cvt_pk_bf16_f32 v152, v152, v153
	v_cvt_pk_bf16_f32 v153, v154, v155
	global_store_dwordx2 v[168:169], v[152:153], off offset:288
	s_and_saveexec_b64 s[42:43], s[6:7]
	s_cbranch_execz .LBB0_1612
	v_lshl_add_u64 v[152:153], v[136:137], 2, s[24:25]
	s_waitcnt lgkmcnt(0)
	v_add_f32_e32 v137, v140, v141
	v_mov_b32_e32 v208, v137
	v_mov_b64_e32 v[172:173], v[152:153]
.LBB0_1612:
	s_or_b64 exec, exec, s[42:43]
	v_or_b32_e32 v140, 16, v136
	s_waitcnt lgkmcnt(0)
	v_ashrrev_i32_e32 v141, 31, v140
	v_lshlrev_b64 v[152:153], 12, v[140:141]
	v_lshl_add_u64 v[152:153], s[16:17], 0, v[152:153]
	v_lshl_add_u64 v[168:169], v[138:139], 2, v[152:153]
	global_load_dwordx4 v[152:155], v[168:169], off
	global_load_dwordx4 v[196:199], v[168:169], off offset:64
	global_load_dwordx4 v[200:203], v[168:169], off offset:512
	global_load_dwordx4 v[204:207], v[168:169], off offset:576
	v_lshlrev_b64 v[156:157], 11, v[140:141]
	v_lshl_add_u64 v[156:157], s[22:23], 0, v[156:157]
	v_lshl_add_u64 v[170:171], v[138:139], 1, v[156:157]
	s_waitcnt vmcnt(3) lgkmcnt(0)
	v_pk_add_f32 v[154:155], v[118:119], v[154:155]
	v_pk_add_f32 v[152:153], v[116:117], v[152:153]
	global_store_dwordx4 v[168:169], v[152:155], off sc1
	v_cvt_pk_bf16_f32 v156, v152, v153
	v_cvt_pk_bf16_f32 v157, v154, v155
	global_store_dwordx2 v[170:171], v[156:157], off
	v_mul_f32_e32 v137, v153, v153
	v_mul_f32_e32 v151, v155, v155
	v_fmac_f32_e32 v137, v152, v152
	v_fmac_f32_e32 v151, v154, v154
	v_add_f32_e32 v137, v137, v151
	s_waitcnt vmcnt(4) lgkmcnt(0)
	v_pk_add_f32 v[198:199], v[114:115], v[198:199]
	v_pk_add_f32 v[196:197], v[112:113], v[196:197]
	global_store_dwordx4 v[168:169], v[196:199], off offset:64 sc1
	v_cvt_pk_bf16_f32 v160, v196, v197
	v_cvt_pk_bf16_f32 v161, v198, v199
	global_store_dwordx2 v[170:171], v[160:161], off offset:32
	v_mul_f32_e32 v151, v197, v197
	v_mul_f32_e32 v152, v199, v199
	v_fmac_f32_e32 v151, v196, v196
	v_fmac_f32_e32 v152, v198, v198
	v_add_f32_e32 v151, v151, v152
	v_add_f32_e32 v137, v137, v151
	s_waitcnt vmcnt(5) lgkmcnt(0)
	v_pk_add_f32 v[202:203], v[94:95], v[202:203]
	v_pk_add_f32 v[200:201], v[92:93], v[200:201]
	global_store_dwordx4 v[168:169], v[200:203], off offset:512 sc1
	v_cvt_pk_bf16_f32 v164, v200, v201
	v_cvt_pk_bf16_f32 v165, v202, v203
	global_store_dwordx2 v[170:171], v[164:165], off offset:256
	v_mul_f32_e32 v151, v201, v201
	v_mul_f32_e32 v152, v203, v203
	v_fmac_f32_e32 v151, v200, v200
	v_fmac_f32_e32 v152, v202, v202
	v_add_f32_e32 v151, v151, v152
	v_add_f32_e32 v137, v137, v151
	s_waitcnt vmcnt(6) lgkmcnt(0)
	v_pk_add_f32 v[154:155], v[86:87], v[206:207]
	v_pk_add_f32 v[152:153], v[84:85], v[204:205]
	v_mul_f32_e32 v156, v155, v155
	v_mul_f32_e32 v151, v153, v153
	v_fmac_f32_e32 v151, v152, v152
	v_fmac_f32_e32 v156, v154, v154
	v_add_f32_e32 v151, v151, v156
	v_add_f32_e32 v137, v137, v151
	ds_bpermute_b32 v151, v149, v137
	global_store_dwordx4 v[168:169], v[152:155], off offset:576 sc1
	s_waitcnt lgkmcnt(0)
	v_add_f32_e32 v137, v137, v151
	ds_bpermute_b32 v151, v150, v137
	v_cvt_pk_bf16_f32 v152, v152, v153
	v_cvt_pk_bf16_f32 v153, v154, v155
	global_store_dwordx2 v[170:171], v[152:153], off offset:288
	s_and_saveexec_b64 s[42:43], s[6:7]
	s_cbranch_execz .LBB0_1614
	v_lshl_add_u64 v[140:141], v[140:141], 2, s[24:25]
	s_waitcnt lgkmcnt(0)
	v_add_f32_e32 v137, v137, v151
	v_mov_b32_e32 v209, v137
.LBB0_1614:
	s_or_b64 exec, exec, s[42:43]
	v_or_b32_e32 v140, 32, v136
	v_ashrrev_i32_e32 v141, 31, v140
	v_lshlrev_b64 v[152:153], 12, v[140:141]
	v_lshl_add_u64 v[152:153], s[16:17], 0, v[152:153]
	v_lshl_add_u64 v[168:169], v[138:139], 2, v[152:153]
	global_load_dwordx4 v[152:155], v[168:169], off
	global_load_dwordx4 v[184:187], v[168:169], off offset:64
	global_load_dwordx4 v[188:191], v[168:169], off offset:512
	global_load_dwordx4 v[192:195], v[168:169], off offset:576
	v_lshlrev_b64 v[156:157], 11, v[140:141]
	v_lshl_add_u64 v[156:157], s[22:23], 0, v[156:157]
	v_lshl_add_u64 v[170:171], v[138:139], 1, v[156:157]
	s_waitcnt vmcnt(3) lgkmcnt(0)
	v_pk_add_f32 v[154:155], v[106:107], v[154:155]
	v_pk_add_f32 v[152:153], v[104:105], v[152:153]
	global_store_dwordx4 v[168:169], v[152:155], off sc1
	v_cvt_pk_bf16_f32 v156, v152, v153
	v_cvt_pk_bf16_f32 v157, v154, v155
	global_store_dwordx2 v[170:171], v[156:157], off
	v_mul_f32_e32 v137, v153, v153
	v_mul_f32_e32 v151, v155, v155
	v_fmac_f32_e32 v137, v152, v152
	v_fmac_f32_e32 v151, v154, v154
	v_add_f32_e32 v137, v137, v151
	s_waitcnt vmcnt(4) lgkmcnt(0)
	v_pk_add_f32 v[186:187], v[98:99], v[186:187]
	v_pk_add_f32 v[184:185], v[96:97], v[184:185]
	global_store_dwordx4 v[168:169], v[184:187], off offset:64 sc1
	v_cvt_pk_bf16_f32 v160, v184, v185
	v_cvt_pk_bf16_f32 v161, v186, v187
	global_store_dwordx2 v[170:171], v[160:161], off offset:32
	v_mul_f32_e32 v151, v185, v185
	v_mul_f32_e32 v152, v187, v187
	v_fmac_f32_e32 v151, v184, v184
	v_fmac_f32_e32 v152, v186, v186
	v_add_f32_e32 v151, v151, v152
	v_add_f32_e32 v137, v137, v151
	s_waitcnt vmcnt(5) lgkmcnt(0)
	v_pk_add_f32 v[190:191], v[78:79], v[190:191]
	v_pk_add_f32 v[188:189], v[76:77], v[188:189]
	global_store_dwordx4 v[168:169], v[188:191], off offset:512 sc1
	v_cvt_pk_bf16_f32 v164, v188, v189
	v_cvt_pk_bf16_f32 v165, v190, v191
	global_store_dwordx2 v[170:171], v[164:165], off offset:256
	v_mul_f32_e32 v151, v189, v189
	v_mul_f32_e32 v152, v191, v191
	v_fmac_f32_e32 v151, v188, v188
	v_fmac_f32_e32 v152, v190, v190
	v_add_f32_e32 v151, v151, v152
	v_add_f32_e32 v137, v137, v151
	s_waitcnt vmcnt(6) lgkmcnt(0)
	v_pk_add_f32 v[154:155], v[74:75], v[194:195]
	v_pk_add_f32 v[152:153], v[72:73], v[192:193]
	v_mul_f32_e32 v156, v155, v155
	v_mul_f32_e32 v151, v153, v153
	v_fmac_f32_e32 v151, v152, v152
	v_fmac_f32_e32 v156, v154, v154
	v_add_f32_e32 v151, v151, v156
	v_add_f32_e32 v137, v137, v151
	ds_bpermute_b32 v151, v149, v137
	global_store_dwordx4 v[168:169], v[152:155], off offset:576 sc1
	s_waitcnt lgkmcnt(0)
	v_add_f32_e32 v137, v137, v151
	ds_bpermute_b32 v151, v150, v137
	v_cvt_pk_bf16_f32 v152, v152, v153
	v_cvt_pk_bf16_f32 v153, v154, v155
	global_store_dwordx2 v[170:171], v[152:153], off offset:288
	s_and_saveexec_b64 s[42:43], s[6:7]
	s_cbranch_execz .LBB0_1616
	v_lshl_add_u64 v[140:141], v[140:141], 2, s[24:25]
	s_waitcnt lgkmcnt(0)
	v_add_f32_e32 v137, v137, v151
	v_mov_b32_e32 v210, v137
.LBB0_1616:
	s_or_b64 exec, exec, s[42:43]
	v_or_b32_e32 v140, 48, v136
	v_ashrrev_i32_e32 v141, 31, v140
	v_lshlrev_b64 v[152:153], 12, v[140:141]
	v_lshl_add_u64 v[152:153], s[16:17], 0, v[152:153]
	v_lshl_add_u64 v[168:169], v[138:139], 2, v[152:153]
	global_load_dwordx4 v[152:155], v[168:169], off
	global_load_dwordx4 v[196:199], v[168:169], off offset:64
	global_load_dwordx4 v[200:203], v[168:169], off offset:512
	global_load_dwordx4 v[204:207], v[168:169], off offset:576
	v_lshlrev_b64 v[156:157], 11, v[140:141]
	v_lshl_add_u64 v[156:157], s[22:23], 0, v[156:157]
	v_lshl_add_u64 v[170:171], v[138:139], 1, v[156:157]
	s_waitcnt vmcnt(3) lgkmcnt(0)
	v_pk_add_f32 v[154:155], v[90:91], v[154:155]
	v_pk_add_f32 v[152:153], v[88:89], v[152:153]
	global_store_dwordx4 v[168:169], v[152:155], off sc1
	v_cvt_pk_bf16_f32 v156, v152, v153
	v_cvt_pk_bf16_f32 v157, v154, v155
	global_store_dwordx2 v[170:171], v[156:157], off
	v_mul_f32_e32 v137, v153, v153
	v_mul_f32_e32 v151, v155, v155
	v_fmac_f32_e32 v137, v152, v152
	v_fmac_f32_e32 v151, v154, v154
	v_add_f32_e32 v137, v137, v151
	s_waitcnt vmcnt(4) lgkmcnt(0)
	v_pk_add_f32 v[198:199], v[82:83], v[198:199]
	v_pk_add_f32 v[196:197], v[80:81], v[196:197]
	global_store_dwordx4 v[168:169], v[196:199], off offset:64 sc1
	v_cvt_pk_bf16_f32 v160, v196, v197
	v_cvt_pk_bf16_f32 v161, v198, v199
	global_store_dwordx2 v[170:171], v[160:161], off offset:32
	v_mul_f32_e32 v151, v197, v197
	v_mul_f32_e32 v152, v199, v199
	v_fmac_f32_e32 v151, v196, v196
	v_fmac_f32_e32 v152, v198, v198
	v_add_f32_e32 v151, v151, v152
	v_add_f32_e32 v137, v137, v151
	s_waitcnt vmcnt(5) lgkmcnt(0)
	v_pk_add_f32 v[202:203], v[70:71], v[202:203]
	v_pk_add_f32 v[200:201], v[68:69], v[200:201]
	global_store_dwordx4 v[168:169], v[200:203], off offset:512 sc1
	v_cvt_pk_bf16_f32 v164, v200, v201
	v_cvt_pk_bf16_f32 v165, v202, v203
	global_store_dwordx2 v[170:171], v[164:165], off offset:256
	v_mul_f32_e32 v151, v201, v201
	v_mul_f32_e32 v152, v203, v203
	v_fmac_f32_e32 v151, v200, v200
	v_fmac_f32_e32 v152, v202, v202
	v_add_f32_e32 v151, v151, v152
	v_add_f32_e32 v137, v137, v151
	s_waitcnt vmcnt(6) lgkmcnt(0)
	v_pk_add_f32 v[154:155], v[66:67], v[206:207]
	v_pk_add_f32 v[152:153], v[64:65], v[204:205]
	v_mul_f32_e32 v156, v155, v155
	v_mul_f32_e32 v151, v153, v153
	v_fmac_f32_e32 v151, v152, v152
	v_fmac_f32_e32 v156, v154, v154
	v_add_f32_e32 v151, v151, v156
	v_add_f32_e32 v137, v137, v151
	ds_bpermute_b32 v151, v149, v137
	global_store_dwordx4 v[168:169], v[152:155], off offset:576 sc1
	s_waitcnt lgkmcnt(0)
	v_add_f32_e32 v137, v137, v151
	ds_bpermute_b32 v151, v150, v137
	v_cvt_pk_bf16_f32 v152, v152, v153
	v_cvt_pk_bf16_f32 v153, v154, v155
	global_store_dwordx2 v[170:171], v[152:153], off offset:288
	s_and_saveexec_b64 s[42:43], s[6:7]
	s_cbranch_execz .LBB0_1618
	v_lshl_add_u64 v[140:141], v[140:141], 2, s[24:25]
	s_waitcnt lgkmcnt(0)
	v_add_f32_e32 v137, v137, v151
	v_mov_b32_e32 v211, v137
.LBB0_1618:
	s_or_b64 exec, exec, s[42:43]
	v_add_u32_e32 v140, 0x80, v136
	v_ashrrev_i32_e32 v141, 31, v140
	v_lshlrev_b64 v[152:153], 12, v[140:141]
	v_lshl_add_u64 v[152:153], s[16:17], 0, v[152:153]
	v_lshl_add_u64 v[168:169], v[138:139], 2, v[152:153]
	global_load_dwordx4 v[152:155], v[168:169], off
	global_load_dwordx4 v[184:187], v[168:169], off offset:64
	global_load_dwordx4 v[188:191], v[168:169], off offset:512
	global_load_dwordx4 v[192:195], v[168:169], off offset:576
	v_lshlrev_b64 v[156:157], 11, v[140:141]
	v_lshl_add_u64 v[156:157], s[22:23], 0, v[156:157]
	v_lshl_add_u64 v[170:171], v[138:139], 1, v[156:157]
	s_waitcnt vmcnt(3) lgkmcnt(0)
	v_pk_add_f32 v[154:155], v[62:63], v[154:155]
	v_pk_add_f32 v[152:153], v[60:61], v[152:153]
	global_store_dwordx4 v[168:169], v[152:155], off sc1
	v_cvt_pk_bf16_f32 v156, v152, v153
	v_cvt_pk_bf16_f32 v157, v154, v155
	global_store_dwordx2 v[170:171], v[156:157], off
	v_mul_f32_e32 v137, v153, v153
	v_mul_f32_e32 v151, v155, v155
	v_fmac_f32_e32 v137, v152, v152
	v_fmac_f32_e32 v151, v154, v154
	v_add_f32_e32 v137, v137, v151
	s_waitcnt vmcnt(4) lgkmcnt(0)
	v_pk_add_f32 v[186:187], v[58:59], v[186:187]
	v_pk_add_f32 v[184:185], v[56:57], v[184:185]
	global_store_dwordx4 v[168:169], v[184:187], off offset:64 sc1
	v_cvt_pk_bf16_f32 v160, v184, v185
	v_cvt_pk_bf16_f32 v161, v186, v187
	global_store_dwordx2 v[170:171], v[160:161], off offset:32
	v_mul_f32_e32 v151, v185, v185
	v_mul_f32_e32 v152, v187, v187
	v_fmac_f32_e32 v151, v184, v184
	v_fmac_f32_e32 v152, v186, v186
	v_add_f32_e32 v151, v151, v152
	v_add_f32_e32 v137, v137, v151
	s_waitcnt vmcnt(5) lgkmcnt(0)
	v_pk_add_f32 v[190:191], v[46:47], v[190:191]
	v_pk_add_f32 v[188:189], v[44:45], v[188:189]
	global_store_dwordx4 v[168:169], v[188:191], off offset:512 sc1
	v_cvt_pk_bf16_f32 v164, v188, v189
	v_cvt_pk_bf16_f32 v165, v190, v191
	global_store_dwordx2 v[170:171], v[164:165], off offset:256
	v_mul_f32_e32 v151, v189, v189
	v_mul_f32_e32 v152, v191, v191
	v_fmac_f32_e32 v151, v188, v188
	v_fmac_f32_e32 v152, v190, v190
	v_add_f32_e32 v151, v151, v152
	v_add_f32_e32 v137, v137, v151
	s_waitcnt vmcnt(6) lgkmcnt(0)
	v_pk_add_f32 v[154:155], v[38:39], v[194:195]
	v_pk_add_f32 v[152:153], v[36:37], v[192:193]
	v_mul_f32_e32 v156, v155, v155
	v_mul_f32_e32 v151, v153, v153
	v_fmac_f32_e32 v151, v152, v152
	v_fmac_f32_e32 v156, v154, v154
	v_add_f32_e32 v151, v151, v156
	v_add_f32_e32 v137, v137, v151
	ds_bpermute_b32 v151, v149, v137
	global_store_dwordx4 v[168:169], v[152:155], off offset:576 sc1
	s_waitcnt lgkmcnt(0)
	v_add_f32_e32 v137, v137, v151
	ds_bpermute_b32 v151, v150, v137
	v_cvt_pk_bf16_f32 v152, v152, v153
	v_cvt_pk_bf16_f32 v153, v154, v155
	global_store_dwordx2 v[170:171], v[152:153], off offset:288
	s_and_saveexec_b64 s[42:43], s[6:7]
	s_cbranch_execz .LBB0_1620
	v_lshl_add_u64 v[140:141], v[140:141], 2, s[24:25]
	s_waitcnt lgkmcnt(0)
	v_add_f32_e32 v137, v137, v151
	v_mov_b32_e32 v212, v137
.LBB0_1620:
	s_or_b64 exec, exec, s[42:43]
	v_add_u32_e32 v140, 0x90, v136
	v_ashrrev_i32_e32 v141, 31, v140
	v_lshlrev_b64 v[152:153], 12, v[140:141]
	v_lshl_add_u64 v[152:153], s[16:17], 0, v[152:153]
	v_lshl_add_u64 v[168:169], v[138:139], 2, v[152:153]
	global_load_dwordx4 v[152:155], v[168:169], off
	global_load_dwordx4 v[196:199], v[168:169], off offset:64
	global_load_dwordx4 v[200:203], v[168:169], off offset:512
	global_load_dwordx4 v[204:207], v[168:169], off offset:576
	v_lshlrev_b64 v[156:157], 11, v[140:141]
	v_lshl_add_u64 v[156:157], s[22:23], 0, v[156:157]
	v_lshl_add_u64 v[170:171], v[138:139], 1, v[156:157]
	s_waitcnt vmcnt(3) lgkmcnt(0)
	v_pk_add_f32 v[154:155], v[54:55], v[154:155]
	v_pk_add_f32 v[152:153], v[52:53], v[152:153]
	global_store_dwordx4 v[168:169], v[152:155], off sc1
	v_cvt_pk_bf16_f32 v156, v152, v153
	v_cvt_pk_bf16_f32 v157, v154, v155
	global_store_dwordx2 v[170:171], v[156:157], off
	v_mul_f32_e32 v137, v153, v153
	v_mul_f32_e32 v151, v155, v155
	v_fmac_f32_e32 v137, v152, v152
	v_fmac_f32_e32 v151, v154, v154
	v_add_f32_e32 v137, v137, v151
	s_waitcnt vmcnt(4) lgkmcnt(0)
	v_pk_add_f32 v[198:199], v[50:51], v[198:199]
	v_pk_add_f32 v[196:197], v[48:49], v[196:197]
	global_store_dwordx4 v[168:169], v[196:199], off offset:64 sc1
	v_cvt_pk_bf16_f32 v160, v196, v197
	v_cvt_pk_bf16_f32 v161, v198, v199
	global_store_dwordx2 v[170:171], v[160:161], off offset:32
	v_mul_f32_e32 v151, v197, v197
	v_mul_f32_e32 v152, v199, v199
	v_fmac_f32_e32 v151, v196, v196
	v_fmac_f32_e32 v152, v198, v198
	v_add_f32_e32 v151, v151, v152
	v_add_f32_e32 v137, v137, v151
	s_waitcnt vmcnt(5) lgkmcnt(0)
	v_pk_add_f32 v[202:203], v[30:31], v[202:203]
	v_pk_add_f32 v[200:201], v[28:29], v[200:201]
	global_store_dwordx4 v[168:169], v[200:203], off offset:512 sc1
	v_cvt_pk_bf16_f32 v164, v200, v201
	v_cvt_pk_bf16_f32 v165, v202, v203
	global_store_dwordx2 v[170:171], v[164:165], off offset:256
	v_mul_f32_e32 v151, v201, v201
	v_mul_f32_e32 v152, v203, v203
	v_fmac_f32_e32 v151, v200, v200
	v_fmac_f32_e32 v152, v202, v202
	v_add_f32_e32 v151, v151, v152
	v_add_f32_e32 v137, v137, v151
	s_waitcnt vmcnt(6) lgkmcnt(0)
	v_pk_add_f32 v[154:155], v[22:23], v[206:207]
	v_pk_add_f32 v[152:153], v[20:21], v[204:205]
	v_mul_f32_e32 v156, v155, v155
	v_mul_f32_e32 v151, v153, v153
	v_fmac_f32_e32 v151, v152, v152
	v_fmac_f32_e32 v156, v154, v154
	v_add_f32_e32 v151, v151, v156
	v_add_f32_e32 v137, v137, v151
	ds_bpermute_b32 v151, v149, v137
	global_store_dwordx4 v[168:169], v[152:155], off offset:576 sc1
	s_waitcnt lgkmcnt(0)
	v_add_f32_e32 v137, v137, v151
	ds_bpermute_b32 v151, v150, v137
	v_cvt_pk_bf16_f32 v152, v152, v153
	v_cvt_pk_bf16_f32 v153, v154, v155
	global_store_dwordx2 v[170:171], v[152:153], off offset:288
	s_and_saveexec_b64 s[42:43], s[6:7]
	s_cbranch_execz .LBB0_1622
	v_lshl_add_u64 v[140:141], v[140:141], 2, s[24:25]
	s_waitcnt lgkmcnt(0)
	v_add_f32_e32 v137, v137, v151
	v_mov_b32_e32 v213, v137
.LBB0_1622:
	s_or_b64 exec, exec, s[42:43]
	v_add_u32_e32 v140, 0xa0, v136
	v_ashrrev_i32_e32 v141, 31, v140
	v_lshlrev_b64 v[152:153], 12, v[140:141]
	v_lshl_add_u64 v[152:153], s[16:17], 0, v[152:153]
	v_lshl_add_u64 v[168:169], v[138:139], 2, v[152:153]
	global_load_dwordx4 v[152:155], v[168:169], off
	global_load_dwordx4 v[184:187], v[168:169], off offset:64
	global_load_dwordx4 v[188:191], v[168:169], off offset:512
	global_load_dwordx4 v[192:195], v[168:169], off offset:576
	v_lshlrev_b64 v[156:157], 11, v[140:141]
	v_lshl_add_u64 v[156:157], s[22:23], 0, v[156:157]
	v_lshl_add_u64 v[170:171], v[138:139], 1, v[156:157]
	s_waitcnt vmcnt(3) lgkmcnt(0)
	v_pk_add_f32 v[154:155], v[42:43], v[154:155]
	v_pk_add_f32 v[152:153], v[40:41], v[152:153]
	global_store_dwordx4 v[168:169], v[152:155], off sc1
	v_cvt_pk_bf16_f32 v156, v152, v153
	v_cvt_pk_bf16_f32 v157, v154, v155
	global_store_dwordx2 v[170:171], v[156:157], off
	v_mul_f32_e32 v137, v153, v153
	v_mul_f32_e32 v151, v155, v155
	v_fmac_f32_e32 v137, v152, v152
	v_fmac_f32_e32 v151, v154, v154
	v_add_f32_e32 v137, v137, v151
	s_waitcnt vmcnt(4) lgkmcnt(0)
	v_pk_add_f32 v[186:187], v[34:35], v[186:187]
	v_pk_add_f32 v[184:185], v[32:33], v[184:185]
	global_store_dwordx4 v[168:169], v[184:187], off offset:64 sc1
	v_cvt_pk_bf16_f32 v160, v184, v185
	v_cvt_pk_bf16_f32 v161, v186, v187
	global_store_dwordx2 v[170:171], v[160:161], off offset:32
	v_mul_f32_e32 v151, v185, v185
	v_mul_f32_e32 v152, v187, v187
	v_fmac_f32_e32 v151, v184, v184
	v_fmac_f32_e32 v152, v186, v186
	v_add_f32_e32 v151, v151, v152
	v_add_f32_e32 v137, v137, v151
	s_waitcnt vmcnt(5) lgkmcnt(0)
	v_pk_add_f32 v[190:191], v[14:15], v[190:191]
	v_pk_add_f32 v[188:189], v[12:13], v[188:189]
	global_store_dwordx4 v[168:169], v[188:191], off offset:512 sc1
	v_cvt_pk_bf16_f32 v164, v188, v189
	v_cvt_pk_bf16_f32 v165, v190, v191
	global_store_dwordx2 v[170:171], v[164:165], off offset:256
	v_mul_f32_e32 v151, v189, v189
	v_mul_f32_e32 v152, v191, v191
	v_fmac_f32_e32 v151, v188, v188
	v_fmac_f32_e32 v152, v190, v190
	v_add_f32_e32 v151, v151, v152
	v_add_f32_e32 v137, v137, v151
	s_waitcnt vmcnt(6) lgkmcnt(0)
	v_pk_add_f32 v[154:155], v[10:11], v[194:195]
	v_pk_add_f32 v[152:153], v[8:9], v[192:193]
	v_mul_f32_e32 v156, v155, v155
	v_mul_f32_e32 v151, v153, v153
	v_fmac_f32_e32 v151, v152, v152
	v_fmac_f32_e32 v156, v154, v154
	v_add_f32_e32 v151, v151, v156
	v_add_f32_e32 v137, v137, v151
	ds_bpermute_b32 v151, v149, v137
	global_store_dwordx4 v[168:169], v[152:155], off offset:576 sc1
	s_waitcnt lgkmcnt(0)
	v_add_f32_e32 v137, v137, v151
	ds_bpermute_b32 v151, v150, v137
	v_cvt_pk_bf16_f32 v152, v152, v153
	v_cvt_pk_bf16_f32 v153, v154, v155
	global_store_dwordx2 v[170:171], v[152:153], off offset:288
	s_and_saveexec_b64 s[42:43], s[6:7]
	s_cbranch_execz .LBB0_1624
	v_lshl_add_u64 v[140:141], v[140:141], 2, s[24:25]
	s_waitcnt lgkmcnt(0)
	v_add_f32_e32 v137, v137, v151
	v_mov_b32_e32 v214, v137
.LBB0_1624:
	s_or_b64 exec, exec, s[42:43]
	v_add_u32_e32 v140, 0xb0, v136
	v_ashrrev_i32_e32 v141, 31, v140
	v_lshlrev_b64 v[152:153], 12, v[140:141]
	v_lshl_add_u64 v[152:153], s[16:17], 0, v[152:153]
	v_lshl_add_u64 v[168:169], v[138:139], 2, v[152:153]
	global_load_dwordx4 v[152:155], v[168:169], off
	global_load_dwordx4 v[196:199], v[168:169], off offset:64
	global_load_dwordx4 v[200:203], v[168:169], off offset:512
	global_load_dwordx4 v[204:207], v[168:169], off offset:576
	v_lshlrev_b64 v[156:157], 11, v[140:141]
	v_lshl_add_u64 v[156:157], s[22:23], 0, v[156:157]
	v_lshl_add_u64 v[170:171], v[138:139], 1, v[156:157]
	s_waitcnt vmcnt(3) lgkmcnt(0)
	v_pk_add_f32 v[154:155], v[26:27], v[154:155]
	v_pk_add_f32 v[152:153], v[24:25], v[152:153]
	global_store_dwordx4 v[168:169], v[152:155], off sc1
	v_cvt_pk_bf16_f32 v156, v152, v153
	v_cvt_pk_bf16_f32 v157, v154, v155
	global_store_dwordx2 v[170:171], v[156:157], off
	v_mul_f32_e32 v137, v153, v153
	v_mul_f32_e32 v151, v155, v155
	v_fmac_f32_e32 v137, v152, v152
	v_fmac_f32_e32 v151, v154, v154
	v_add_f32_e32 v137, v137, v151
	s_waitcnt vmcnt(4) lgkmcnt(0)
	v_pk_add_f32 v[198:199], v[18:19], v[198:199]
	v_pk_add_f32 v[196:197], v[16:17], v[196:197]
	global_store_dwordx4 v[168:169], v[196:199], off offset:64 sc1
	v_cvt_pk_bf16_f32 v160, v196, v197
	v_cvt_pk_bf16_f32 v161, v198, v199
	global_store_dwordx2 v[170:171], v[160:161], off offset:32
	v_mul_f32_e32 v151, v197, v197
	v_mul_f32_e32 v152, v199, v199
	v_fmac_f32_e32 v151, v196, v196
	v_fmac_f32_e32 v152, v198, v198
	v_add_f32_e32 v151, v151, v152
	v_add_f32_e32 v137, v137, v151
	s_waitcnt vmcnt(5) lgkmcnt(0)
	v_pk_add_f32 v[202:203], v[6:7], v[202:203]
	v_pk_add_f32 v[200:201], v[4:5], v[200:201]
	global_store_dwordx4 v[168:169], v[200:203], off offset:512 sc1
	v_cvt_pk_bf16_f32 v164, v200, v201
	v_cvt_pk_bf16_f32 v165, v202, v203
	global_store_dwordx2 v[170:171], v[164:165], off offset:256
	v_mul_f32_e32 v151, v201, v201
	v_mul_f32_e32 v152, v203, v203
	v_fmac_f32_e32 v151, v200, v200
	v_fmac_f32_e32 v152, v202, v202
	v_add_f32_e32 v151, v151, v152
	v_add_f32_e32 v137, v137, v151
	s_waitcnt vmcnt(6) lgkmcnt(0)
	v_pk_add_f32 v[154:155], v[2:3], v[206:207]
	v_pk_add_f32 v[152:153], v[0:1], v[204:205]
	v_mul_f32_e32 v156, v155, v155
	v_mul_f32_e32 v151, v153, v153
	v_fmac_f32_e32 v151, v152, v152
	v_fmac_f32_e32 v156, v154, v154
	v_add_f32_e32 v151, v151, v156
	v_add_f32_e32 v137, v137, v151
	ds_bpermute_b32 v149, v149, v137
	global_store_dwordx4 v[168:169], v[152:155], off offset:576 sc1
	s_waitcnt lgkmcnt(0)
	v_add_f32_e32 v137, v137, v149
	ds_bpermute_b32 v149, v150, v137
	v_cvt_pk_bf16_f32 v150, v152, v153
	v_cvt_pk_bf16_f32 v151, v154, v155
	global_store_dwordx2 v[170:171], v[150:151], off offset:288
	s_and_saveexec_b64 s[42:43], s[6:7]
	s_cbranch_execz .LBB0_1626
	v_lshl_add_u64 v[140:141], v[140:141], 2, s[24:25]
	s_waitcnt lgkmcnt(0)
	v_add_f32_e32 v137, v137, v149
	v_mov_b32_e32 v215, v137

.LBB0_1837:
	v_ashrrev_i32_e32 v137, 31, v136
	v_lshlrev_b64 v[140:141], 12, v[136:137]
	v_lshl_add_u64 v[140:141], s[16:17], 0, v[140:141]
	v_lshl_add_u64 v[166:167], v[138:139], 2, v[140:141]
	global_load_dwordx4 v[150:153], v[166:167], off
	global_load_dwordx4 v[184:187], v[166:167], off offset:64
	global_load_dwordx4 v[188:191], v[166:167], off offset:512
	global_load_dwordx4 v[192:195], v[166:167], off offset:576
	v_lshlrev_b64 v[140:141], 11, v[136:137]
	v_lshl_add_u64 v[140:141], s[22:23], 0, v[140:141]
	v_lshl_add_u64 v[168:169], v[138:139], 1, v[140:141]
	s_waitcnt vmcnt(3) lgkmcnt(0)
	v_pk_fma_f32 v[152:153], v[126:127], 0.5, v[152:153] op_sel_hi:[1,0,1]
	v_pk_fma_f32 v[150:151], v[124:125], 0.5, v[150:151] op_sel_hi:[1,0,1]
	global_store_dwordx4 v[166:167], v[150:153], off sc1
	v_cvt_pk_bf16_f32 v140, v150, v151
	v_cvt_pk_bf16_f32 v141, v152, v153
	global_store_dwordx2 v[168:169], v[140:141], off
	s_waitcnt vmcnt(4) lgkmcnt(0)
	v_pk_fma_f32 v[186:187], v[122:123], 0.5, v[186:187] op_sel_hi:[1,0,1]
	v_pk_fma_f32 v[184:185], v[120:121], 0.5, v[184:185] op_sel_hi:[1,0,1]
	global_store_dwordx4 v[166:167], v[184:187], off offset:64 sc1
	v_cvt_pk_bf16_f32 v140, v184, v185
	v_cvt_pk_bf16_f32 v141, v186, v187
	global_store_dwordx2 v[168:169], v[140:141], off offset:32
	s_waitcnt vmcnt(5) lgkmcnt(0)
	v_pk_fma_f32 v[190:191], v[118:119], 0.5, v[190:191] op_sel_hi:[1,0,1]
	v_pk_fma_f32 v[188:189], v[116:117], 0.5, v[188:189] op_sel_hi:[1,0,1]
	global_store_dwordx4 v[166:167], v[188:191], off offset:512 sc1
	v_cvt_pk_bf16_f32 v140, v188, v189
	v_cvt_pk_bf16_f32 v141, v190, v191
	global_store_dwordx2 v[168:169], v[140:141], off offset:256
	v_and_b32_e32 v141, 64, v148
	v_xor_b32_e32 v140, 16, v148
	v_add_u32_e32 v141, 64, v141
	v_cmp_lt_i32_e32 vcc, v140, v141
	s_nop 1
	v_cndmask_b32_e32 v140, v148, v140, vcc
	v_lshlrev_b32_e32 v149, 2, v140
	v_mul_f32_e32 v140, v151, v151
	v_mul_f32_e32 v151, v153, v153
	v_fmac_f32_e32 v140, v150, v150
	v_fmac_f32_e32 v151, v152, v152
	v_add_f32_e32 v140, v140, v151
	v_mul_f32_e32 v150, v185, v185
	v_mul_f32_e32 v151, v187, v187
	v_fmac_f32_e32 v150, v184, v184
	v_fmac_f32_e32 v151, v186, v186
	v_add_f32_e32 v150, v150, v151
	v_add_f32_e32 v140, v140, v150
	v_mul_f32_e32 v150, v189, v189
	v_mul_f32_e32 v151, v191, v191
	v_fmac_f32_e32 v150, v188, v188
	v_fmac_f32_e32 v151, v190, v190
	v_add_f32_e32 v150, v150, v151
	v_add_f32_e32 v140, v140, v150
	s_waitcnt vmcnt(6) lgkmcnt(0)
	v_pk_fma_f32 v[154:155], v[114:115], 0.5, v[194:195] op_sel_hi:[1,0,1]
	v_pk_fma_f32 v[152:153], v[112:113], 0.5, v[192:193] op_sel_hi:[1,0,1]
	v_mul_f32_e32 v151, v155, v155
	v_mul_f32_e32 v150, v153, v153
	v_fmac_f32_e32 v150, v152, v152
	v_fmac_f32_e32 v151, v154, v154
	v_add_f32_e32 v150, v150, v151
	v_add_f32_e32 v140, v140, v150
	ds_bpermute_b32 v150, v149, v140
	v_xor_b32_e32 v151, 32, v148
	v_cmp_lt_i32_e32 vcc, v151, v141
	global_store_dwordx4 v[166:167], v[152:155], off offset:576 sc1
	s_waitcnt lgkmcnt(0)
	v_add_f32_e32 v140, v140, v150
	v_cndmask_b32_e32 v141, v148, v151, vcc
	v_lshlrev_b32_e32 v150, 2, v141
	ds_bpermute_b32 v141, v150, v140
	v_cvt_pk_bf16_f32 v152, v152, v153
	v_cvt_pk_bf16_f32 v153, v154, v155
	global_store_dwordx2 v[168:169], v[152:153], off offset:288
	s_and_saveexec_b64 s[38:39], s[6:7]
	s_cbranch_execz .LBB0_1839
	v_lshl_add_u64 v[152:153], v[136:137], 2, s[24:25]
	s_waitcnt lgkmcnt(0)
	v_add_f32_e32 v137, v140, v141
	v_mov_b32_e32 v208, v137
	v_mov_b64_e32 v[172:173], v[152:153]
.LBB0_1839:
	s_or_b64 exec, exec, s[38:39]
	v_or_b32_e32 v140, 16, v136
	s_waitcnt lgkmcnt(0)
	v_ashrrev_i32_e32 v141, 31, v140
	v_lshlrev_b64 v[152:153], 12, v[140:141]
	v_lshl_add_u64 v[152:153], s[16:17], 0, v[152:153]
	v_lshl_add_u64 v[168:169], v[138:139], 2, v[152:153]
	global_load_dwordx4 v[152:155], v[168:169], off
	global_load_dwordx4 v[196:199], v[168:169], off offset:64
	global_load_dwordx4 v[200:203], v[168:169], off offset:512
	global_load_dwordx4 v[204:207], v[168:169], off offset:576
	v_lshlrev_b64 v[156:157], 11, v[140:141]
	v_lshl_add_u64 v[156:157], s[22:23], 0, v[156:157]
	v_lshl_add_u64 v[170:171], v[138:139], 1, v[156:157]
	s_waitcnt vmcnt(3) lgkmcnt(0)
	v_pk_fma_f32 v[154:155], v[110:111], 0.5, v[154:155] op_sel_hi:[1,0,1]
	v_pk_fma_f32 v[152:153], v[108:109], 0.5, v[152:153] op_sel_hi:[1,0,1]
	global_store_dwordx4 v[168:169], v[152:155], off sc1
	v_cvt_pk_bf16_f32 v156, v152, v153
	v_cvt_pk_bf16_f32 v157, v154, v155
	global_store_dwordx2 v[170:171], v[156:157], off
	v_mul_f32_e32 v137, v153, v153
	v_mul_f32_e32 v151, v155, v155
	v_fmac_f32_e32 v137, v152, v152
	v_fmac_f32_e32 v151, v154, v154
	v_add_f32_e32 v137, v137, v151
	s_waitcnt vmcnt(4) lgkmcnt(0)
	v_pk_fma_f32 v[198:199], v[106:107], 0.5, v[198:199] op_sel_hi:[1,0,1]
	v_pk_fma_f32 v[196:197], v[104:105], 0.5, v[196:197] op_sel_hi:[1,0,1]
	global_store_dwordx4 v[168:169], v[196:199], off offset:64 sc1
	v_cvt_pk_bf16_f32 v160, v196, v197
	v_cvt_pk_bf16_f32 v161, v198, v199
	global_store_dwordx2 v[170:171], v[160:161], off offset:32
	v_mul_f32_e32 v151, v197, v197
	v_mul_f32_e32 v152, v199, v199
	v_fmac_f32_e32 v151, v196, v196
	v_fmac_f32_e32 v152, v198, v198
	v_add_f32_e32 v151, v151, v152
	v_add_f32_e32 v137, v137, v151
	s_waitcnt vmcnt(5) lgkmcnt(0)
	v_pk_fma_f32 v[202:203], v[102:103], 0.5, v[202:203] op_sel_hi:[1,0,1]
	v_pk_fma_f32 v[200:201], v[100:101], 0.5, v[200:201] op_sel_hi:[1,0,1]
	global_store_dwordx4 v[168:169], v[200:203], off offset:512 sc1
	v_cvt_pk_bf16_f32 v164, v200, v201
	v_cvt_pk_bf16_f32 v165, v202, v203
	global_store_dwordx2 v[170:171], v[164:165], off offset:256
	v_mul_f32_e32 v151, v201, v201
	v_mul_f32_e32 v152, v203, v203
	v_fmac_f32_e32 v151, v200, v200
	v_fmac_f32_e32 v152, v202, v202
	v_add_f32_e32 v151, v151, v152
	v_add_f32_e32 v137, v137, v151
	s_waitcnt vmcnt(6) lgkmcnt(0)
	v_pk_fma_f32 v[154:155], v[98:99], 0.5, v[206:207] op_sel_hi:[1,0,1]
	v_pk_fma_f32 v[152:153], v[96:97], 0.5, v[204:205] op_sel_hi:[1,0,1]
	v_mul_f32_e32 v156, v155, v155
	v_mul_f32_e32 v151, v153, v153
	v_fmac_f32_e32 v151, v152, v152
	v_fmac_f32_e32 v156, v154, v154
	v_add_f32_e32 v151, v151, v156
	v_add_f32_e32 v137, v137, v151
	ds_bpermute_b32 v151, v149, v137
	global_store_dwordx4 v[168:169], v[152:155], off offset:576 sc1
	s_waitcnt lgkmcnt(0)
	v_add_f32_e32 v137, v137, v151
	ds_bpermute_b32 v151, v150, v137
	v_cvt_pk_bf16_f32 v152, v152, v153
	v_cvt_pk_bf16_f32 v153, v154, v155
	global_store_dwordx2 v[170:171], v[152:153], off offset:288
	s_and_saveexec_b64 s[38:39], s[6:7]
	s_cbranch_execz .LBB0_1841
	v_lshl_add_u64 v[140:141], v[140:141], 2, s[24:25]
	s_waitcnt lgkmcnt(0)
	v_add_f32_e32 v137, v137, v151
	v_mov_b32_e32 v209, v137
.LBB0_1841:
	s_or_b64 exec, exec, s[38:39]
	v_or_b32_e32 v140, 32, v136
	v_ashrrev_i32_e32 v141, 31, v140
	v_lshlrev_b64 v[152:153], 12, v[140:141]
	v_lshl_add_u64 v[152:153], s[16:17], 0, v[152:153]
	v_lshl_add_u64 v[168:169], v[138:139], 2, v[152:153]
	global_load_dwordx4 v[152:155], v[168:169], off
	global_load_dwordx4 v[184:187], v[168:169], off offset:64
	global_load_dwordx4 v[188:191], v[168:169], off offset:512
	global_load_dwordx4 v[192:195], v[168:169], off offset:576
	v_lshlrev_b64 v[156:157], 11, v[140:141]
	v_lshl_add_u64 v[156:157], s[22:23], 0, v[156:157]
	v_lshl_add_u64 v[170:171], v[138:139], 1, v[156:157]
	s_waitcnt vmcnt(3) lgkmcnt(0)
	v_pk_fma_f32 v[154:155], v[94:95], 0.5, v[154:155] op_sel_hi:[1,0,1]
	v_pk_fma_f32 v[152:153], v[92:93], 0.5, v[152:153] op_sel_hi:[1,0,1]
	global_store_dwordx4 v[168:169], v[152:155], off sc1
	v_cvt_pk_bf16_f32 v156, v152, v153
	v_cvt_pk_bf16_f32 v157, v154, v155
	global_store_dwordx2 v[170:171], v[156:157], off
	v_mul_f32_e32 v137, v153, v153
	v_mul_f32_e32 v151, v155, v155
	v_fmac_f32_e32 v137, v152, v152
	v_fmac_f32_e32 v151, v154, v154
	v_add_f32_e32 v137, v137, v151
	s_waitcnt vmcnt(4) lgkmcnt(0)
	v_pk_fma_f32 v[186:187], v[90:91], 0.5, v[186:187] op_sel_hi:[1,0,1]
	v_pk_fma_f32 v[184:185], v[88:89], 0.5, v[184:185] op_sel_hi:[1,0,1]
	global_store_dwordx4 v[168:169], v[184:187], off offset:64 sc1
	v_cvt_pk_bf16_f32 v160, v184, v185
	v_cvt_pk_bf16_f32 v161, v186, v187
	global_store_dwordx2 v[170:171], v[160:161], off offset:32
	v_mul_f32_e32 v151, v185, v185
	v_mul_f32_e32 v152, v187, v187
	v_fmac_f32_e32 v151, v184, v184
	v_fmac_f32_e32 v152, v186, v186
	v_add_f32_e32 v151, v151, v152
	v_add_f32_e32 v137, v137, v151
	s_waitcnt vmcnt(5) lgkmcnt(0)
	v_pk_fma_f32 v[190:191], v[86:87], 0.5, v[190:191] op_sel_hi:[1,0,1]
	v_pk_fma_f32 v[188:189], v[84:85], 0.5, v[188:189] op_sel_hi:[1,0,1]
	global_store_dwordx4 v[168:169], v[188:191], off offset:512 sc1
	v_cvt_pk_bf16_f32 v164, v188, v189
	v_cvt_pk_bf16_f32 v165, v190, v191
	global_store_dwordx2 v[170:171], v[164:165], off offset:256
	v_mul_f32_e32 v151, v189, v189
	v_mul_f32_e32 v152, v191, v191
	v_fmac_f32_e32 v151, v188, v188
	v_fmac_f32_e32 v152, v190, v190
	v_add_f32_e32 v151, v151, v152
	v_add_f32_e32 v137, v137, v151
	s_waitcnt vmcnt(6) lgkmcnt(0)
	v_pk_fma_f32 v[154:155], v[82:83], 0.5, v[194:195] op_sel_hi:[1,0,1]
	v_pk_fma_f32 v[152:153], v[80:81], 0.5, v[192:193] op_sel_hi:[1,0,1]
	v_mul_f32_e32 v156, v155, v155
	v_mul_f32_e32 v151, v153, v153
	v_fmac_f32_e32 v151, v152, v152
	v_fmac_f32_e32 v156, v154, v154
	v_add_f32_e32 v151, v151, v156
	v_add_f32_e32 v137, v137, v151
	ds_bpermute_b32 v151, v149, v137
	global_store_dwordx4 v[168:169], v[152:155], off offset:576 sc1
	s_waitcnt lgkmcnt(0)
	v_add_f32_e32 v137, v137, v151
	ds_bpermute_b32 v151, v150, v137
	v_cvt_pk_bf16_f32 v152, v152, v153
	v_cvt_pk_bf16_f32 v153, v154, v155
	global_store_dwordx2 v[170:171], v[152:153], off offset:288
	s_and_saveexec_b64 s[38:39], s[6:7]
	s_cbranch_execz .LBB0_1843
	v_lshl_add_u64 v[140:141], v[140:141], 2, s[24:25]
	s_waitcnt lgkmcnt(0)
	v_add_f32_e32 v137, v137, v151
	v_mov_b32_e32 v210, v137
.LBB0_1843:
	s_or_b64 exec, exec, s[38:39]
	v_or_b32_e32 v140, 48, v136
	v_ashrrev_i32_e32 v141, 31, v140
	v_lshlrev_b64 v[152:153], 12, v[140:141]
	v_lshl_add_u64 v[152:153], s[16:17], 0, v[152:153]
	v_lshl_add_u64 v[168:169], v[138:139], 2, v[152:153]
	global_load_dwordx4 v[152:155], v[168:169], off
	global_load_dwordx4 v[196:199], v[168:169], off offset:64
	global_load_dwordx4 v[200:203], v[168:169], off offset:512
	global_load_dwordx4 v[204:207], v[168:169], off offset:576
	v_lshlrev_b64 v[156:157], 11, v[140:141]
	v_lshl_add_u64 v[156:157], s[22:23], 0, v[156:157]
	v_lshl_add_u64 v[170:171], v[138:139], 1, v[156:157]
	s_waitcnt vmcnt(3) lgkmcnt(0)
	v_pk_fma_f32 v[154:155], v[78:79], 0.5, v[154:155] op_sel_hi:[1,0,1]
	v_pk_fma_f32 v[152:153], v[76:77], 0.5, v[152:153] op_sel_hi:[1,0,1]
	global_store_dwordx4 v[168:169], v[152:155], off sc1
	v_cvt_pk_bf16_f32 v156, v152, v153
	v_cvt_pk_bf16_f32 v157, v154, v155
	global_store_dwordx2 v[170:171], v[156:157], off
	v_mul_f32_e32 v137, v153, v153
	v_mul_f32_e32 v151, v155, v155
	v_fmac_f32_e32 v137, v152, v152
	v_fmac_f32_e32 v151, v154, v154
	v_add_f32_e32 v137, v137, v151
	s_waitcnt vmcnt(4) lgkmcnt(0)
	v_pk_fma_f32 v[198:199], v[74:75], 0.5, v[198:199] op_sel_hi:[1,0,1]
	v_pk_fma_f32 v[196:197], v[72:73], 0.5, v[196:197] op_sel_hi:[1,0,1]
	global_store_dwordx4 v[168:169], v[196:199], off offset:64 sc1
	v_cvt_pk_bf16_f32 v160, v196, v197
	v_cvt_pk_bf16_f32 v161, v198, v199
	global_store_dwordx2 v[170:171], v[160:161], off offset:32
	v_mul_f32_e32 v151, v197, v197
	v_mul_f32_e32 v152, v199, v199
	v_fmac_f32_e32 v151, v196, v196
	v_fmac_f32_e32 v152, v198, v198
	v_add_f32_e32 v151, v151, v152
	v_add_f32_e32 v137, v137, v151
	s_waitcnt vmcnt(5) lgkmcnt(0)
	v_pk_fma_f32 v[202:203], v[70:71], 0.5, v[202:203] op_sel_hi:[1,0,1]
	v_pk_fma_f32 v[200:201], v[68:69], 0.5, v[200:201] op_sel_hi:[1,0,1]
	global_store_dwordx4 v[168:169], v[200:203], off offset:512 sc1
	v_cvt_pk_bf16_f32 v164, v200, v201
	v_cvt_pk_bf16_f32 v165, v202, v203
	global_store_dwordx2 v[170:171], v[164:165], off offset:256
	v_mul_f32_e32 v151, v201, v201
	v_mul_f32_e32 v152, v203, v203
	v_fmac_f32_e32 v151, v200, v200
	v_fmac_f32_e32 v152, v202, v202
	v_add_f32_e32 v151, v151, v152
	v_add_f32_e32 v137, v137, v151
	s_waitcnt vmcnt(6) lgkmcnt(0)
	v_pk_fma_f32 v[154:155], v[66:67], 0.5, v[206:207] op_sel_hi:[1,0,1]
	v_pk_fma_f32 v[152:153], v[64:65], 0.5, v[204:205] op_sel_hi:[1,0,1]
	v_mul_f32_e32 v156, v155, v155
	v_mul_f32_e32 v151, v153, v153
	v_fmac_f32_e32 v151, v152, v152
	v_fmac_f32_e32 v156, v154, v154
	v_add_f32_e32 v151, v151, v156
	v_add_f32_e32 v137, v137, v151
	ds_bpermute_b32 v151, v149, v137
	global_store_dwordx4 v[168:169], v[152:155], off offset:576 sc1
	s_waitcnt lgkmcnt(0)
	v_add_f32_e32 v137, v137, v151
	ds_bpermute_b32 v151, v150, v137
	v_cvt_pk_bf16_f32 v152, v152, v153
	v_cvt_pk_bf16_f32 v153, v154, v155
	global_store_dwordx2 v[170:171], v[152:153], off offset:288
	s_and_saveexec_b64 s[38:39], s[6:7]
	s_cbranch_execz .LBB0_1845
	v_lshl_add_u64 v[140:141], v[140:141], 2, s[24:25]
	s_waitcnt lgkmcnt(0)
	v_add_f32_e32 v137, v137, v151
	v_mov_b32_e32 v211, v137
.LBB0_1845:
	s_or_b64 exec, exec, s[38:39]
	v_add_u32_e32 v140, 0x80, v136
	v_ashrrev_i32_e32 v141, 31, v140
	v_lshlrev_b64 v[152:153], 12, v[140:141]
	v_lshl_add_u64 v[152:153], s[16:17], 0, v[152:153]
	v_lshl_add_u64 v[168:169], v[138:139], 2, v[152:153]
	global_load_dwordx4 v[152:155], v[168:169], off
	global_load_dwordx4 v[184:187], v[168:169], off offset:64
	global_load_dwordx4 v[188:191], v[168:169], off offset:512
	global_load_dwordx4 v[192:195], v[168:169], off offset:576
	v_lshlrev_b64 v[156:157], 11, v[140:141]
	v_lshl_add_u64 v[156:157], s[22:23], 0, v[156:157]
	v_lshl_add_u64 v[170:171], v[138:139], 1, v[156:157]
	s_waitcnt vmcnt(3) lgkmcnt(0)
	v_pk_fma_f32 v[154:155], v[62:63], 0.5, v[154:155] op_sel_hi:[1,0,1]
	v_pk_fma_f32 v[152:153], v[60:61], 0.5, v[152:153] op_sel_hi:[1,0,1]
	global_store_dwordx4 v[168:169], v[152:155], off sc1
	v_cvt_pk_bf16_f32 v156, v152, v153
	v_cvt_pk_bf16_f32 v157, v154, v155
	global_store_dwordx2 v[170:171], v[156:157], off
	v_mul_f32_e32 v137, v153, v153
	v_mul_f32_e32 v151, v155, v155
	v_fmac_f32_e32 v137, v152, v152
	v_fmac_f32_e32 v151, v154, v154
	v_add_f32_e32 v137, v137, v151
	s_waitcnt vmcnt(4) lgkmcnt(0)
	v_pk_fma_f32 v[186:187], v[58:59], 0.5, v[186:187] op_sel_hi:[1,0,1]
	v_pk_fma_f32 v[184:185], v[56:57], 0.5, v[184:185] op_sel_hi:[1,0,1]
	global_store_dwordx4 v[168:169], v[184:187], off offset:64 sc1
	v_cvt_pk_bf16_f32 v160, v184, v185
	v_cvt_pk_bf16_f32 v161, v186, v187
	global_store_dwordx2 v[170:171], v[160:161], off offset:32
	v_mul_f32_e32 v151, v185, v185
	v_mul_f32_e32 v152, v187, v187
	v_fmac_f32_e32 v151, v184, v184
	v_fmac_f32_e32 v152, v186, v186
	v_add_f32_e32 v151, v151, v152
	v_add_f32_e32 v137, v137, v151
	s_waitcnt vmcnt(5) lgkmcnt(0)
	v_pk_fma_f32 v[190:191], v[54:55], 0.5, v[190:191] op_sel_hi:[1,0,1]
	v_pk_fma_f32 v[188:189], v[52:53], 0.5, v[188:189] op_sel_hi:[1,0,1]
	global_store_dwordx4 v[168:169], v[188:191], off offset:512 sc1
	v_cvt_pk_bf16_f32 v164, v188, v189
	v_cvt_pk_bf16_f32 v165, v190, v191
	global_store_dwordx2 v[170:171], v[164:165], off offset:256
	v_mul_f32_e32 v151, v189, v189
	v_mul_f32_e32 v152, v191, v191
	v_fmac_f32_e32 v151, v188, v188
	v_fmac_f32_e32 v152, v190, v190
	v_add_f32_e32 v151, v151, v152
	v_add_f32_e32 v137, v137, v151
	s_waitcnt vmcnt(6) lgkmcnt(0)
	v_pk_fma_f32 v[154:155], v[50:51], 0.5, v[194:195] op_sel_hi:[1,0,1]
	v_pk_fma_f32 v[152:153], v[48:49], 0.5, v[192:193] op_sel_hi:[1,0,1]
	v_mul_f32_e32 v156, v155, v155
	v_mul_f32_e32 v151, v153, v153
	v_fmac_f32_e32 v151, v152, v152
	v_fmac_f32_e32 v156, v154, v154
	v_add_f32_e32 v151, v151, v156
	v_add_f32_e32 v137, v137, v151
	ds_bpermute_b32 v151, v149, v137
	global_store_dwordx4 v[168:169], v[152:155], off offset:576 sc1
	s_waitcnt lgkmcnt(0)
	v_add_f32_e32 v137, v137, v151
	ds_bpermute_b32 v151, v150, v137
	v_cvt_pk_bf16_f32 v152, v152, v153
	v_cvt_pk_bf16_f32 v153, v154, v155
	global_store_dwordx2 v[170:171], v[152:153], off offset:288
	s_and_saveexec_b64 s[38:39], s[6:7]
	s_cbranch_execz .LBB0_1847
	v_lshl_add_u64 v[140:141], v[140:141], 2, s[24:25]
	s_waitcnt lgkmcnt(0)
	v_add_f32_e32 v137, v137, v151
	v_mov_b32_e32 v212, v137
.LBB0_1847:
	s_or_b64 exec, exec, s[38:39]
	v_add_u32_e32 v140, 0x90, v136
	v_ashrrev_i32_e32 v141, 31, v140
	v_lshlrev_b64 v[152:153], 12, v[140:141]
	v_lshl_add_u64 v[152:153], s[16:17], 0, v[152:153]
	v_lshl_add_u64 v[168:169], v[138:139], 2, v[152:153]
	global_load_dwordx4 v[152:155], v[168:169], off
	global_load_dwordx4 v[196:199], v[168:169], off offset:64
	global_load_dwordx4 v[200:203], v[168:169], off offset:512
	global_load_dwordx4 v[204:207], v[168:169], off offset:576
	v_lshlrev_b64 v[156:157], 11, v[140:141]
	v_lshl_add_u64 v[156:157], s[22:23], 0, v[156:157]
	v_lshl_add_u64 v[170:171], v[138:139], 1, v[156:157]
	s_waitcnt vmcnt(3) lgkmcnt(0)
	v_pk_fma_f32 v[154:155], v[46:47], 0.5, v[154:155] op_sel_hi:[1,0,1]
	v_pk_fma_f32 v[152:153], v[44:45], 0.5, v[152:153] op_sel_hi:[1,0,1]
	global_store_dwordx4 v[168:169], v[152:155], off sc1
	v_cvt_pk_bf16_f32 v156, v152, v153
	v_cvt_pk_bf16_f32 v157, v154, v155
	global_store_dwordx2 v[170:171], v[156:157], off
	v_mul_f32_e32 v137, v153, v153
	v_mul_f32_e32 v151, v155, v155
	v_fmac_f32_e32 v137, v152, v152
	v_fmac_f32_e32 v151, v154, v154
	v_add_f32_e32 v137, v137, v151
	s_waitcnt vmcnt(4) lgkmcnt(0)
	v_pk_fma_f32 v[198:199], v[42:43], 0.5, v[198:199] op_sel_hi:[1,0,1]
	v_pk_fma_f32 v[196:197], v[40:41], 0.5, v[196:197] op_sel_hi:[1,0,1]
	global_store_dwordx4 v[168:169], v[196:199], off offset:64 sc1
	v_cvt_pk_bf16_f32 v160, v196, v197
	v_cvt_pk_bf16_f32 v161, v198, v199
	global_store_dwordx2 v[170:171], v[160:161], off offset:32
	v_mul_f32_e32 v151, v197, v197
	v_mul_f32_e32 v152, v199, v199
	v_fmac_f32_e32 v151, v196, v196
	v_fmac_f32_e32 v152, v198, v198
	v_add_f32_e32 v151, v151, v152
	v_add_f32_e32 v137, v137, v151
	s_waitcnt vmcnt(5) lgkmcnt(0)
	v_pk_fma_f32 v[202:203], v[38:39], 0.5, v[202:203] op_sel_hi:[1,0,1]
	v_pk_fma_f32 v[200:201], v[36:37], 0.5, v[200:201] op_sel_hi:[1,0,1]
	global_store_dwordx4 v[168:169], v[200:203], off offset:512 sc1
	v_cvt_pk_bf16_f32 v164, v200, v201
	v_cvt_pk_bf16_f32 v165, v202, v203
	global_store_dwordx2 v[170:171], v[164:165], off offset:256
	v_mul_f32_e32 v151, v201, v201
	v_mul_f32_e32 v152, v203, v203
	v_fmac_f32_e32 v151, v200, v200
	v_fmac_f32_e32 v152, v202, v202
	v_add_f32_e32 v151, v151, v152
	v_add_f32_e32 v137, v137, v151
	s_waitcnt vmcnt(6) lgkmcnt(0)
	v_pk_fma_f32 v[154:155], v[34:35], 0.5, v[206:207] op_sel_hi:[1,0,1]
	v_pk_fma_f32 v[152:153], v[32:33], 0.5, v[204:205] op_sel_hi:[1,0,1]
	v_mul_f32_e32 v156, v155, v155
	v_mul_f32_e32 v151, v153, v153
	v_fmac_f32_e32 v151, v152, v152
	v_fmac_f32_e32 v156, v154, v154
	v_add_f32_e32 v151, v151, v156
	v_add_f32_e32 v137, v137, v151
	ds_bpermute_b32 v151, v149, v137
	global_store_dwordx4 v[168:169], v[152:155], off offset:576 sc1
	s_waitcnt lgkmcnt(0)
	v_add_f32_e32 v137, v137, v151
	ds_bpermute_b32 v151, v150, v137
	v_cvt_pk_bf16_f32 v152, v152, v153
	v_cvt_pk_bf16_f32 v153, v154, v155
	global_store_dwordx2 v[170:171], v[152:153], off offset:288
	s_and_saveexec_b64 s[38:39], s[6:7]
	s_cbranch_execz .LBB0_1849
	v_lshl_add_u64 v[140:141], v[140:141], 2, s[24:25]
	s_waitcnt lgkmcnt(0)
	v_add_f32_e32 v137, v137, v151
	v_mov_b32_e32 v213, v137
.LBB0_1849:
	s_or_b64 exec, exec, s[38:39]
	v_add_u32_e32 v140, 0xa0, v136
	v_ashrrev_i32_e32 v141, 31, v140
	v_lshlrev_b64 v[152:153], 12, v[140:141]
	v_lshl_add_u64 v[152:153], s[16:17], 0, v[152:153]
	v_lshl_add_u64 v[168:169], v[138:139], 2, v[152:153]
	global_load_dwordx4 v[152:155], v[168:169], off
	global_load_dwordx4 v[184:187], v[168:169], off offset:64
	global_load_dwordx4 v[188:191], v[168:169], off offset:512
	global_load_dwordx4 v[192:195], v[168:169], off offset:576
	v_lshlrev_b64 v[156:157], 11, v[140:141]
	v_lshl_add_u64 v[156:157], s[22:23], 0, v[156:157]
	v_lshl_add_u64 v[170:171], v[138:139], 1, v[156:157]
	s_waitcnt vmcnt(3) lgkmcnt(0)
	v_pk_fma_f32 v[154:155], v[30:31], 0.5, v[154:155] op_sel_hi:[1,0,1]
	v_pk_fma_f32 v[152:153], v[28:29], 0.5, v[152:153] op_sel_hi:[1,0,1]
	global_store_dwordx4 v[168:169], v[152:155], off sc1
	v_cvt_pk_bf16_f32 v156, v152, v153
	v_cvt_pk_bf16_f32 v157, v154, v155
	global_store_dwordx2 v[170:171], v[156:157], off
	v_mul_f32_e32 v137, v153, v153
	v_mul_f32_e32 v151, v155, v155
	v_fmac_f32_e32 v137, v152, v152
	v_fmac_f32_e32 v151, v154, v154
	v_add_f32_e32 v137, v137, v151
	s_waitcnt vmcnt(4) lgkmcnt(0)
	v_pk_fma_f32 v[186:187], v[26:27], 0.5, v[186:187] op_sel_hi:[1,0,1]
	v_pk_fma_f32 v[184:185], v[24:25], 0.5, v[184:185] op_sel_hi:[1,0,1]
	global_store_dwordx4 v[168:169], v[184:187], off offset:64 sc1
	v_cvt_pk_bf16_f32 v160, v184, v185
	v_cvt_pk_bf16_f32 v161, v186, v187
	global_store_dwordx2 v[170:171], v[160:161], off offset:32
	v_mul_f32_e32 v151, v185, v185
	v_mul_f32_e32 v152, v187, v187
	v_fmac_f32_e32 v151, v184, v184
	v_fmac_f32_e32 v152, v186, v186
	v_add_f32_e32 v151, v151, v152
	v_add_f32_e32 v137, v137, v151
	s_waitcnt vmcnt(5) lgkmcnt(0)
	v_pk_fma_f32 v[190:191], v[22:23], 0.5, v[190:191] op_sel_hi:[1,0,1]
	v_pk_fma_f32 v[188:189], v[20:21], 0.5, v[188:189] op_sel_hi:[1,0,1]
	global_store_dwordx4 v[168:169], v[188:191], off offset:512 sc1
	v_cvt_pk_bf16_f32 v164, v188, v189
	v_cvt_pk_bf16_f32 v165, v190, v191
	global_store_dwordx2 v[170:171], v[164:165], off offset:256
	v_mul_f32_e32 v151, v189, v189
	v_mul_f32_e32 v152, v191, v191
	v_fmac_f32_e32 v151, v188, v188
	v_fmac_f32_e32 v152, v190, v190
	v_add_f32_e32 v151, v151, v152
	v_add_f32_e32 v137, v137, v151
	s_waitcnt vmcnt(6) lgkmcnt(0)
	v_pk_fma_f32 v[154:155], v[18:19], 0.5, v[194:195] op_sel_hi:[1,0,1]
	v_pk_fma_f32 v[152:153], v[16:17], 0.5, v[192:193] op_sel_hi:[1,0,1]
	v_mul_f32_e32 v156, v155, v155
	v_mul_f32_e32 v151, v153, v153
	v_fmac_f32_e32 v151, v152, v152
	v_fmac_f32_e32 v156, v154, v154
	v_add_f32_e32 v151, v151, v156
	v_add_f32_e32 v137, v137, v151
	ds_bpermute_b32 v151, v149, v137
	global_store_dwordx4 v[168:169], v[152:155], off offset:576 sc1
	s_waitcnt lgkmcnt(0)
	v_add_f32_e32 v137, v137, v151
	ds_bpermute_b32 v151, v150, v137
	v_cvt_pk_bf16_f32 v152, v152, v153
	v_cvt_pk_bf16_f32 v153, v154, v155
	global_store_dwordx2 v[170:171], v[152:153], off offset:288
	s_and_saveexec_b64 s[38:39], s[6:7]
	s_cbranch_execz .LBB0_1851
	v_lshl_add_u64 v[140:141], v[140:141], 2, s[24:25]
	s_waitcnt lgkmcnt(0)
	v_add_f32_e32 v137, v137, v151
	v_mov_b32_e32 v214, v137
.LBB0_1851:
	s_or_b64 exec, exec, s[38:39]
	v_add_u32_e32 v140, 0xb0, v136
	v_ashrrev_i32_e32 v141, 31, v140
	v_lshlrev_b64 v[152:153], 12, v[140:141]
	v_lshl_add_u64 v[152:153], s[16:17], 0, v[152:153]
	v_lshl_add_u64 v[168:169], v[138:139], 2, v[152:153]
	global_load_dwordx4 v[152:155], v[168:169], off
	global_load_dwordx4 v[196:199], v[168:169], off offset:64
	global_load_dwordx4 v[200:203], v[168:169], off offset:512
	global_load_dwordx4 v[204:207], v[168:169], off offset:576
	v_lshlrev_b64 v[156:157], 11, v[140:141]
	v_lshl_add_u64 v[156:157], s[22:23], 0, v[156:157]
	v_lshl_add_u64 v[170:171], v[138:139], 1, v[156:157]
	s_waitcnt vmcnt(3) lgkmcnt(0)
	v_pk_fma_f32 v[154:155], v[14:15], 0.5, v[154:155] op_sel_hi:[1,0,1]
	v_pk_fma_f32 v[152:153], v[12:13], 0.5, v[152:153] op_sel_hi:[1,0,1]
	global_store_dwordx4 v[168:169], v[152:155], off sc1
	v_cvt_pk_bf16_f32 v156, v152, v153
	v_cvt_pk_bf16_f32 v157, v154, v155
	global_store_dwordx2 v[170:171], v[156:157], off
	v_mul_f32_e32 v137, v153, v153
	v_mul_f32_e32 v151, v155, v155
	v_fmac_f32_e32 v137, v152, v152
	v_fmac_f32_e32 v151, v154, v154
	v_add_f32_e32 v137, v137, v151
	s_waitcnt vmcnt(4) lgkmcnt(0)
	v_pk_fma_f32 v[198:199], v[10:11], 0.5, v[198:199] op_sel_hi:[1,0,1]
	v_pk_fma_f32 v[196:197], v[8:9], 0.5, v[196:197] op_sel_hi:[1,0,1]
	global_store_dwordx4 v[168:169], v[196:199], off offset:64 sc1
	v_cvt_pk_bf16_f32 v160, v196, v197
	v_cvt_pk_bf16_f32 v161, v198, v199
	global_store_dwordx2 v[170:171], v[160:161], off offset:32
	v_mul_f32_e32 v151, v197, v197
	v_mul_f32_e32 v152, v199, v199
	v_fmac_f32_e32 v151, v196, v196
	v_fmac_f32_e32 v152, v198, v198
	v_add_f32_e32 v151, v151, v152
	v_add_f32_e32 v137, v137, v151
	s_waitcnt vmcnt(5) lgkmcnt(0)
	v_pk_fma_f32 v[202:203], v[6:7], 0.5, v[202:203] op_sel_hi:[1,0,1]
	v_pk_fma_f32 v[200:201], v[4:5], 0.5, v[200:201] op_sel_hi:[1,0,1]
	global_store_dwordx4 v[168:169], v[200:203], off offset:512 sc1
	v_cvt_pk_bf16_f32 v164, v200, v201
	v_cvt_pk_bf16_f32 v165, v202, v203
	global_store_dwordx2 v[170:171], v[164:165], off offset:256
	v_mul_f32_e32 v151, v201, v201
	v_mul_f32_e32 v152, v203, v203
	v_fmac_f32_e32 v151, v200, v200
	v_fmac_f32_e32 v152, v202, v202
	v_add_f32_e32 v151, v151, v152
	v_add_f32_e32 v137, v137, v151
	s_waitcnt vmcnt(6) lgkmcnt(0)
	v_pk_fma_f32 v[154:155], v[2:3], 0.5, v[206:207] op_sel_hi:[1,0,1]
	v_pk_fma_f32 v[152:153], v[0:1], 0.5, v[204:205] op_sel_hi:[1,0,1]
	v_mul_f32_e32 v156, v155, v155
	v_mul_f32_e32 v151, v153, v153
	v_fmac_f32_e32 v151, v152, v152
	v_fmac_f32_e32 v156, v154, v154
	v_add_f32_e32 v151, v151, v156
	v_add_f32_e32 v137, v137, v151
	ds_bpermute_b32 v149, v149, v137
	global_store_dwordx4 v[168:169], v[152:155], off offset:576 sc1
	s_waitcnt lgkmcnt(0)
	v_add_f32_e32 v137, v137, v149
	ds_bpermute_b32 v149, v150, v137
	v_cvt_pk_bf16_f32 v150, v152, v153
	v_cvt_pk_bf16_f32 v151, v154, v155
	global_store_dwordx2 v[170:171], v[150:151], off offset:288
	s_and_saveexec_b64 s[38:39], s[6:7]
	s_cbranch_execz .LBB0_1853
	v_lshl_add_u64 v[140:141], v[140:141], 2, s[24:25]
	s_waitcnt lgkmcnt(0)
	v_add_f32_e32 v137, v137, v149
	v_mov_b32_e32 v215, v137

.LBB0_2254:
	v_lshl_add_u64 v[0:1], s[50:51], 0, v[22:23]
	v_add_co_u32_e32 v0, vcc, 0xe000000, v0
	s_add_i32 s12, s18, 0xffff8000
	s_nop 0
	v_addc_co_u32_e32 v1, vcc, 0, v1, vcc
	global_load_dwordx2 v[2:3], v[0:1], off
	global_load_dwordx2 v[34:35], v[0:1], off offset:512
	global_load_dwordx2 v[36:37], v[0:1], off offset:1024
	global_load_dwordx2 v[38:39], v[6:7], off
	v_lshl_add_u64 v[60:61], s[50:51], 0, v[20:21]
	global_load_dwordx2 v[52:53], v[6:7], off offset:512
	global_load_dwordx2 v[54:55], v[6:7], off offset:1024
	global_load_dwordx4 v[56:59], v[60:61], off
	global_load_dwordx4 v[64:67], v[8:9], off
	s_and_b32 s98, s18, 63
	s_and_b32 s99, s18, 0x1fff
	s_or_b32 s98, s98, 0x400
	s_cmp_lt_i32 s18, 0x8000
	s_cselect_b32 s98, s99, s98
	s_lshl_b32 s98, s98, 8
	s_mov_b32 s99, s13
	v_lshl_add_u64 v[62:63], v[12:13], 0, s[98:99]
	v_lshl_add_u64 v[68:69], s[50:51], 0, v[18:19]
	s_nop 0
	v_add_co_u32_e32 v68, vcc, 0xe000000, v68
	s_nop 1
	v_addc_co_u32_e32 v69, vcc, 0, v69, vcc
	s_and_saveexec_b64 s[100:101], s[6:7]
	global_load_dwordx2 v[70:71], v[62:63], off
	global_load_dword v72, v[68:69], off offset:2688
	global_load_dword v73, v[68:69], off offset:2560
	s_or_b64 exec, exec, s[100:101]
	s_cmp_lt_i32 s18, 0x8000
	s_cselect_b64 s[26:27], -1, 0
	s_mov_b64 s[20:21], s[18:19]
	s_waitcnt vmcnt(7) lgkmcnt(0)
	v_pk_mul_f32 v[0:1], v[2:3], v[2:3]
	v_pk_mul_f32 v[40:41], v[34:35], v[34:35]
	v_pk_mul_f32 v[42:43], v[36:37], v[36:37]
	v_add_f32_e32 v40, v40, v41
	v_add_f32_e32 v0, v0, v1
	v_add_f32_e32 v1, v42, v43
	v_add_f32_e32 v0, v0, v40
	v_add_f32_e32 v0, v0, v1
	ds_bpermute_b32 v1, v26, v0
	s_waitcnt lgkmcnt(0)
	v_add_f32_e32 v0, v0, v1
	ds_bpermute_b32 v1, v27, v0
	s_waitcnt lgkmcnt(0)
	v_add_f32_e32 v0, v0, v1
	ds_bpermute_b32 v1, v28, v0
	s_waitcnt lgkmcnt(0)
	v_add_f32_e32 v0, v0, v1
	ds_bpermute_b32 v1, v29, v0
	s_waitcnt lgkmcnt(0)
	v_add_f32_e32 v0, v0, v1
	ds_bpermute_b32 v1, v30, v0
	s_waitcnt lgkmcnt(0)
	v_add_f32_e32 v0, v0, v1
	ds_bpermute_b32 v1, v31, v0
	s_waitcnt lgkmcnt(0)
	v_add_f32_e32 v0, v0, v1
	v_fmamk_f32 v0, v0, 0x3b2aaaab, v32
	v_mul_f32_e32 v1, 0x4f800000, v0
	v_cmp_gt_f32_e32 vcc, s28, v0
	s_nop 1
	v_cndmask_b32_e32 v40, v0, v1, vcc
	v_sqrt_f32_e32 v41, v40
	v_lshl_add_u64 v[0:1], s[50:51], 0, v[16:17]
	v_add_u32_e32 v42, -1, v41
	v_add_u32_e32 v43, 1, v41
	v_fma_f32 v44, -v42, v41, v40
	v_fma_f32 v45, -v43, v41, v40
	v_cmp_ge_f32_e64 s[8:9], 0, v44
	s_nop 1
	v_cndmask_b32_e64 v41, v41, v42, s[8:9]
	v_cmp_lt_f32_e64 s[8:9], 0, v45
	s_nop 1
	v_cndmask_b32_e64 v41, v41, v43, s[8:9]
	v_mul_f32_e32 v42, 0x37800000, v41
	v_cndmask_b32_e32 v41, v41, v42, vcc
	v_cmp_class_f32_e32 vcc, v40, v33
	s_nop 1
	v_cndmask_b32_e32 v40, v41, v40, vcc
	v_div_scale_f32 v41, s[8:9], v40, v40, 1.0
	v_rcp_f32_e32 v42, v41
	v_add_co_u32_e32 v0, vcc, s29, v0
	s_and_b64 s[8:9], s[26:27], exec
	s_nop 0
	v_addc_co_u32_e32 v1, vcc, 0, v1, vcc
	v_fma_f32 v44, -v41, v42, 1.0
	v_div_scale_f32 v43, vcc, 1.0, v40, 1.0
	v_fmac_f32_e32 v42, v44, v42
	v_mul_f32_e32 v44, v43, v42
	v_fma_f32 v45, -v41, v44, v43
	v_fmac_f32_e32 v44, v45, v42
	v_fma_f32 v41, -v41, v44, v43
	v_div_fmas_f32 v41, v41, v42, v44
	v_div_fixup_f32 v40, v41, v40, 1.0
	v_mul_f32_e32 v2, v2, v40
	v_mul_f32_e32 v3, v3, v40
	v_mul_f32_e32 v2, v38, v2
	v_mul_f32_e32 v3, v39, v3
	v_cvt_pk_bf16_f32 v2, v2, v3
	global_store_dword v[0:1], v2, off
	v_mul_f32_e32 v34, v34, v40
	v_mul_f32_e32 v35, v35, v40
	v_lshl_add_u64 v[38:39], s[50:51], 0, v[20:21]
	s_cselect_b32 s10, s30, 0xc200000
	s_cselect_b32 s23, s19, 0
	s_cselect_b32 s22, s18, s12
	s_waitcnt vmcnt(7) lgkmcnt(0)
	v_mov_b64_e32 v[2:3], v[52:53]
	v_mul_f32_e32 v2, v2, v34
	v_mul_f32_e32 v3, v3, v35
	v_cvt_pk_bf16_f32 v2, v2, v3
	global_store_dword v[0:1], v2, off offset:256
	v_mul_f32_e32 v34, v36, v40
	v_mul_f32_e32 v35, v37, v40
	s_waitcnt vmcnt(7) lgkmcnt(0)
	v_mov_b64_e32 v[2:3], v[54:55]
	v_mul_f32_e32 v2, v2, v34
	v_mul_f32_e32 v3, v3, v35
	v_cvt_pk_bf16_f32 v2, v2, v3
	global_store_dword v[0:1], v2, off offset:512
	s_load_dwordx2 s[24:25], s[0:1], 0xd8
	s_waitcnt lgkmcnt(0)
	s_add_u32 s34, s24, s10
	s_addc_u32 s35, s25, 0
	s_lshl_b64 s[10:11], s[22:23], 10
	s_add_u32 s34, s34, s10
	s_addc_u32 s35, s35, s11
	s_waitcnt vmcnt(6)
	v_mov_b64_e32 v[0:1], v[56:57]
	v_mov_b64_e32 v[2:3], v[58:59]
	v_mov_b64_e32 v[34:35], v[64:65]
	v_mov_b64_e32 v[36:37], v[66:67]
	v_pk_mul_f32 v[38:39], v[2:3], v[2:3]
	v_pk_mul_f32 v[40:41], v[0:1], v[0:1]
	s_nop 0
	v_pk_mov_b32 v[42:43], v[40:41], v[38:39] op_sel:[1,0]
	v_mov_b32_e32 v41, v39
	v_pk_add_f32 v[38:39], v[42:43], v[40:41]
	s_nop 0
	v_add_f32_e32 v38, v38, v39
	ds_bpermute_b32 v39, v26, v38
	s_waitcnt lgkmcnt(0)
	v_add_f32_e32 v38, v38, v39
	ds_bpermute_b32 v39, v27, v38
	s_waitcnt lgkmcnt(0)
	v_add_f32_e32 v38, v38, v39
	ds_bpermute_b32 v39, v28, v38
	s_waitcnt lgkmcnt(0)
	v_add_f32_e32 v38, v38, v39
	ds_bpermute_b32 v39, v29, v38
	s_waitcnt lgkmcnt(0)
	v_add_f32_e32 v38, v38, v39
	ds_bpermute_b32 v39, v30, v38
	s_waitcnt lgkmcnt(0)
	v_add_f32_e32 v38, v38, v39
	ds_bpermute_b32 v39, v31, v38
	s_waitcnt lgkmcnt(0)
	v_add_f32_e32 v38, v38, v39
	v_fmamk_f32 v38, v38, 0x3b800000, v32
	v_mul_f32_e32 v39, 0x4f800000, v38
	v_cmp_gt_f32_e32 vcc, s28, v38
	s_nop 1
	v_cndmask_b32_e32 v38, v38, v39, vcc
	v_sqrt_f32_e32 v39, v38
	s_nop 0
	v_add_u32_e32 v40, -1, v39
	v_add_u32_e32 v41, 1, v39
	v_fma_f32 v42, -v40, v39, v38
	v_fma_f32 v43, -v41, v39, v38
	v_cmp_ge_f32_e64 s[10:11], 0, v42
	s_nop 1
	v_cndmask_b32_e64 v39, v39, v40, s[10:11]
	v_cmp_lt_f32_e64 s[10:11], 0, v43
	s_nop 1
	v_cndmask_b32_e64 v39, v39, v41, s[10:11]
	v_mul_f32_e32 v40, 0x37800000, v39
	v_cndmask_b32_e32 v39, v39, v40, vcc
	v_cmp_class_f32_e32 vcc, v38, v33
	s_nop 1
	v_cndmask_b32_e32 v40, v39, v38, vcc
	v_div_scale_f32 v41, s[10:11], v40, v40, 1.0
	v_rcp_f32_e32 v42, v41
	v_div_scale_f32 v43, vcc, 1.0, v40, 1.0
	v_lshl_add_u64 v[38:39], s[34:35], 0, v[24:25]
	v_fma_f32 v44, -v41, v42, 1.0
	v_fmac_f32_e32 v42, v44, v42
	v_mul_f32_e32 v44, v43, v42
	v_fma_f32 v45, -v41, v44, v43
	v_fmac_f32_e32 v44, v45, v42
	v_fma_f32 v41, -v41, v44, v43
	v_div_fmas_f32 v41, v41, v42, v44
	v_div_fixup_f32 v40, v41, v40, 1.0
	v_pk_mul_f32 v[0:1], v[0:1], v[40:41] op_sel_hi:[1,0]
	v_pk_mul_f32 v[2:3], v[2:3], v[40:41] op_sel_hi:[1,0]
	v_pk_mul_f32 v[0:1], v[34:35], v[0:1]
	v_pk_mul_f32 v[2:3], v[36:37], v[2:3]
	s_mov_b64 vcc, s[8:9]
	global_store_dwordx4 v[38:39], v[0:3], off sc1
	s_cbranch_vccnz .LBB0_2256
	s_lshr_b32 s8, s12, 6
	s_mulk_i32 s8, 0x440
	s_and_b32 s9, s18, 63
	s_or_b32 s8, s8, s9
	s_add_i32 s12, s8, 0x8400
	s_mov_b64 s[20:21], s[12:13]

.LBB0_2899:
	v_ashrrev_i32_e32 v137, 31, v136
	v_lshlrev_b64 v[140:141], 12, v[136:137]
	v_lshl_add_u64 v[140:141], s[14:15], 0, v[140:141]
	v_lshlrev_b64 v[142:143], 2, v[138:139]
	v_lshl_add_u64 v[140:141], v[140:141], 0, v[142:143]
	global_load_dwordx4 v[150:153], v[140:141], off
	global_load_dwordx4 v[184:187], v[140:141], off offset:64
	global_load_dwordx4 v[188:191], v[140:141], off offset:512
	global_load_dwordx4 v[192:195], v[140:141], off offset:576
	s_waitcnt vmcnt(3) lgkmcnt(0)
	v_pk_fma_f32 v[152:153], v[126:127], 0.5, v[152:153] op_sel_hi:[1,0,1]
	v_pk_fma_f32 v[150:151], v[124:125], 0.5, v[150:151] op_sel_hi:[1,0,1]
	global_store_dwordx4 v[140:141], v[150:153], off sc1
	s_waitcnt vmcnt(3) lgkmcnt(0)
	v_pk_fma_f32 v[186:187], v[122:123], 0.5, v[186:187] op_sel_hi:[1,0,1]
	v_pk_fma_f32 v[184:185], v[120:121], 0.5, v[184:185] op_sel_hi:[1,0,1]
	global_store_dwordx4 v[140:141], v[184:187], off offset:64 sc1
	s_waitcnt vmcnt(3) lgkmcnt(0)
	v_pk_fma_f32 v[190:191], v[118:119], 0.5, v[190:191] op_sel_hi:[1,0,1]
	v_pk_fma_f32 v[188:189], v[116:117], 0.5, v[188:189] op_sel_hi:[1,0,1]
	global_store_dwordx4 v[140:141], v[188:191], off offset:512 sc1
	s_waitcnt vmcnt(3) lgkmcnt(0)
	v_pk_fma_f32 v[194:195], v[114:115], 0.5, v[194:195] op_sel_hi:[1,0,1]
	v_pk_fma_f32 v[192:193], v[112:113], 0.5, v[192:193] op_sel_hi:[1,0,1]
	global_store_dwordx4 v[140:141], v[192:195], off offset:576 sc1
	s_nop 1
	v_or_b32_e32 v150, 16, v136
	v_ashrrev_i32_e32 v151, 31, v150
	v_lshlrev_b64 v[150:151], 12, v[150:151]
	v_lshl_add_u64 v[150:151], s[14:15], 0, v[150:151]
	v_lshl_add_u64 v[154:155], v[150:151], 0, v[142:143]
	global_load_dwordx4 v[150:153], v[154:155], off
	global_load_dwordx4 v[196:199], v[154:155], off offset:64
	global_load_dwordx4 v[200:203], v[154:155], off offset:512
	global_load_dwordx4 v[204:207], v[154:155], off offset:576
	s_waitcnt vmcnt(3) lgkmcnt(0)
	v_pk_fma_f32 v[152:153], v[110:111], 0.5, v[152:153] op_sel_hi:[1,0,1]
	v_pk_fma_f32 v[150:151], v[108:109], 0.5, v[150:151] op_sel_hi:[1,0,1]
	global_store_dwordx4 v[154:155], v[150:153], off sc1
	s_waitcnt vmcnt(3) lgkmcnt(0)
	v_pk_fma_f32 v[198:199], v[106:107], 0.5, v[198:199] op_sel_hi:[1,0,1]
	v_pk_fma_f32 v[196:197], v[104:105], 0.5, v[196:197] op_sel_hi:[1,0,1]
	global_store_dwordx4 v[154:155], v[196:199], off offset:64 sc1
	s_waitcnt vmcnt(3) lgkmcnt(0)
	v_pk_fma_f32 v[202:203], v[102:103], 0.5, v[202:203] op_sel_hi:[1,0,1]
	v_pk_fma_f32 v[200:201], v[100:101], 0.5, v[200:201] op_sel_hi:[1,0,1]
	global_store_dwordx4 v[154:155], v[200:203], off offset:512 sc1
	s_waitcnt vmcnt(3) lgkmcnt(0)
	v_pk_fma_f32 v[206:207], v[98:99], 0.5, v[206:207] op_sel_hi:[1,0,1]
	v_pk_fma_f32 v[204:205], v[96:97], 0.5, v[204:205] op_sel_hi:[1,0,1]
	global_store_dwordx4 v[154:155], v[204:207], off offset:576 sc1
	s_nop 1
	v_or_b32_e32 v150, 32, v136
	v_ashrrev_i32_e32 v151, 31, v150
	v_lshlrev_b64 v[150:151], 12, v[150:151]
	v_lshl_add_u64 v[150:151], s[14:15], 0, v[150:151]
	v_lshl_add_u64 v[154:155], v[150:151], 0, v[142:143]
	global_load_dwordx4 v[150:153], v[154:155], off
	global_load_dwordx4 v[184:187], v[154:155], off offset:64
	global_load_dwordx4 v[188:191], v[154:155], off offset:512
	global_load_dwordx4 v[192:195], v[154:155], off offset:576
	s_waitcnt vmcnt(3) lgkmcnt(0)
	v_pk_fma_f32 v[152:153], v[94:95], 0.5, v[152:153] op_sel_hi:[1,0,1]
	v_pk_fma_f32 v[150:151], v[92:93], 0.5, v[150:151] op_sel_hi:[1,0,1]
	global_store_dwordx4 v[154:155], v[150:153], off sc1
	s_waitcnt vmcnt(3) lgkmcnt(0)
	v_pk_fma_f32 v[186:187], v[90:91], 0.5, v[186:187] op_sel_hi:[1,0,1]
	v_pk_fma_f32 v[184:185], v[88:89], 0.5, v[184:185] op_sel_hi:[1,0,1]
	global_store_dwordx4 v[154:155], v[184:187], off offset:64 sc1
	s_waitcnt vmcnt(3) lgkmcnt(0)
	v_pk_fma_f32 v[190:191], v[86:87], 0.5, v[190:191] op_sel_hi:[1,0,1]
	v_pk_fma_f32 v[188:189], v[84:85], 0.5, v[188:189] op_sel_hi:[1,0,1]
	global_store_dwordx4 v[154:155], v[188:191], off offset:512 sc1
	s_waitcnt vmcnt(3) lgkmcnt(0)
	v_pk_fma_f32 v[194:195], v[82:83], 0.5, v[194:195] op_sel_hi:[1,0,1]
	v_pk_fma_f32 v[192:193], v[80:81], 0.5, v[192:193] op_sel_hi:[1,0,1]
	global_store_dwordx4 v[154:155], v[192:195], off offset:576 sc1
	v_add_co_u32_e32 v154, vcc, s81, v140
	s_nop 0
	v_or_b32_e32 v150, 48, v136
	v_ashrrev_i32_e32 v151, 31, v150
	v_lshlrev_b64 v[150:151], 12, v[150:151]
	v_lshl_add_u64 v[150:151], s[14:15], 0, v[150:151]
	v_lshl_add_u64 v[142:143], v[150:151], 0, v[142:143]
	global_load_dwordx4 v[150:153], v[142:143], off
	global_load_dwordx4 v[196:199], v[142:143], off offset:64
	global_load_dwordx4 v[200:203], v[142:143], off offset:512
	global_load_dwordx4 v[204:207], v[142:143], off offset:576
	v_addc_co_u32_e32 v155, vcc, 0, v141, vcc
	s_waitcnt vmcnt(3) lgkmcnt(0)
	v_pk_fma_f32 v[152:153], v[78:79], 0.5, v[152:153] op_sel_hi:[1,0,1]
	v_pk_fma_f32 v[150:151], v[76:77], 0.5, v[150:151] op_sel_hi:[1,0,1]
	global_store_dwordx4 v[142:143], v[150:153], off sc1
	s_waitcnt vmcnt(3) lgkmcnt(0)
	v_pk_fma_f32 v[198:199], v[74:75], 0.5, v[198:199] op_sel_hi:[1,0,1]
	v_pk_fma_f32 v[196:197], v[72:73], 0.5, v[196:197] op_sel_hi:[1,0,1]
	global_store_dwordx4 v[142:143], v[196:199], off offset:64 sc1
	s_waitcnt vmcnt(3) lgkmcnt(0)
	v_pk_fma_f32 v[202:203], v[70:71], 0.5, v[202:203] op_sel_hi:[1,0,1]
	v_pk_fma_f32 v[200:201], v[68:69], 0.5, v[200:201] op_sel_hi:[1,0,1]
	global_store_dwordx4 v[142:143], v[200:203], off offset:512 sc1
	s_waitcnt vmcnt(3) lgkmcnt(0)
	v_pk_fma_f32 v[206:207], v[66:67], 0.5, v[206:207] op_sel_hi:[1,0,1]
	v_pk_fma_f32 v[204:205], v[64:65], 0.5, v[204:205] op_sel_hi:[1,0,1]
	global_store_dwordx4 v[142:143], v[204:207], off offset:576 sc1
	global_load_dwordx4 v[150:153], v[154:155], off
	v_lshl_add_u64 v[142:143], v[140:141], 0, s[26:27]
	global_load_dwordx4 v[184:187], v[142:143], off offset:64
	global_load_dwordx4 v[188:191], v[142:143], off offset:512
	global_load_dwordx4 v[192:195], v[142:143], off offset:576
	s_waitcnt vmcnt(3) lgkmcnt(0)
	v_pk_fma_f32 v[152:153], v[62:63], 0.5, v[152:153] op_sel_hi:[1,0,1]
	v_pk_fma_f32 v[150:151], v[60:61], 0.5, v[150:151] op_sel_hi:[1,0,1]
	global_store_dwordx4 v[154:155], v[150:153], off sc1
	v_add_co_u32_e32 v154, vcc, s82, v140
	s_waitcnt vmcnt(3) lgkmcnt(0)
	v_pk_fma_f32 v[186:187], v[58:59], 0.5, v[186:187] op_sel_hi:[1,0,1]
	v_pk_fma_f32 v[184:185], v[56:57], 0.5, v[184:185] op_sel_hi:[1,0,1]
	global_store_dwordx4 v[142:143], v[184:187], off offset:64 sc1
	v_addc_co_u32_e32 v155, vcc, 0, v141, vcc
	s_waitcnt vmcnt(3) lgkmcnt(0)
	v_pk_fma_f32 v[190:191], v[54:55], 0.5, v[190:191] op_sel_hi:[1,0,1]
	v_pk_fma_f32 v[188:189], v[52:53], 0.5, v[188:189] op_sel_hi:[1,0,1]
	global_store_dwordx4 v[142:143], v[188:191], off offset:512 sc1
	s_waitcnt vmcnt(3) lgkmcnt(0)
	v_pk_fma_f32 v[194:195], v[50:51], 0.5, v[194:195] op_sel_hi:[1,0,1]
	v_pk_fma_f32 v[192:193], v[48:49], 0.5, v[192:193] op_sel_hi:[1,0,1]
	global_store_dwordx4 v[142:143], v[192:195], off offset:576 sc1
	global_load_dwordx4 v[150:153], v[154:155], off
	v_lshl_add_u64 v[142:143], v[140:141], 0, s[28:29]
	global_load_dwordx4 v[196:199], v[142:143], off offset:64
	global_load_dwordx4 v[200:203], v[142:143], off offset:512
	global_load_dwordx4 v[204:207], v[142:143], off offset:576
	s_waitcnt vmcnt(3) lgkmcnt(0)
	v_pk_fma_f32 v[152:153], v[46:47], 0.5, v[152:153] op_sel_hi:[1,0,1]
	v_pk_fma_f32 v[150:151], v[44:45], 0.5, v[150:151] op_sel_hi:[1,0,1]
	global_store_dwordx4 v[154:155], v[150:153], off sc1
	v_add_co_u32_e32 v154, vcc, s83, v140
	s_waitcnt vmcnt(3) lgkmcnt(0)
	v_pk_fma_f32 v[198:199], v[42:43], 0.5, v[198:199] op_sel_hi:[1,0,1]
	v_pk_fma_f32 v[196:197], v[40:41], 0.5, v[196:197] op_sel_hi:[1,0,1]
	global_store_dwordx4 v[142:143], v[196:199], off offset:64 sc1
	v_addc_co_u32_e32 v155, vcc, 0, v141, vcc
	s_waitcnt vmcnt(3) lgkmcnt(0)
	v_pk_fma_f32 v[202:203], v[38:39], 0.5, v[202:203] op_sel_hi:[1,0,1]
	v_pk_fma_f32 v[200:201], v[36:37], 0.5, v[200:201] op_sel_hi:[1,0,1]
	global_store_dwordx4 v[142:143], v[200:203], off offset:512 sc1
	s_waitcnt vmcnt(3) lgkmcnt(0)
	v_pk_fma_f32 v[206:207], v[34:35], 0.5, v[206:207] op_sel_hi:[1,0,1]
	v_pk_fma_f32 v[204:205], v[32:33], 0.5, v[204:205] op_sel_hi:[1,0,1]
	global_store_dwordx4 v[142:143], v[204:207], off offset:576 sc1
	global_load_dwordx4 v[150:153], v[154:155], off
	v_lshl_add_u64 v[142:143], v[140:141], 0, s[30:31]
	global_load_dwordx4 v[184:187], v[142:143], off offset:64
	global_load_dwordx4 v[188:191], v[142:143], off offset:512
	global_load_dwordx4 v[192:195], v[142:143], off offset:576
	s_waitcnt vmcnt(3) lgkmcnt(0)
	v_pk_fma_f32 v[152:153], v[30:31], 0.5, v[152:153] op_sel_hi:[1,0,1]
	v_pk_fma_f32 v[150:151], v[28:29], 0.5, v[150:151] op_sel_hi:[1,0,1]
	global_store_dwordx4 v[154:155], v[150:153], off sc1
	s_waitcnt vmcnt(3) lgkmcnt(0)
	v_pk_fma_f32 v[186:187], v[26:27], 0.5, v[186:187] op_sel_hi:[1,0,1]
	v_pk_fma_f32 v[184:185], v[24:25], 0.5, v[184:185] op_sel_hi:[1,0,1]
	global_store_dwordx4 v[142:143], v[184:187], off offset:64 sc1
	s_waitcnt vmcnt(3) lgkmcnt(0)
	v_pk_fma_f32 v[190:191], v[22:23], 0.5, v[190:191] op_sel_hi:[1,0,1]
	v_pk_fma_f32 v[188:189], v[20:21], 0.5, v[188:189] op_sel_hi:[1,0,1]
	global_store_dwordx4 v[142:143], v[188:191], off offset:512 sc1
	s_waitcnt vmcnt(3) lgkmcnt(0)
	v_pk_fma_f32 v[194:195], v[18:19], 0.5, v[194:195] op_sel_hi:[1,0,1]
	v_pk_fma_f32 v[192:193], v[16:17], 0.5, v[192:193] op_sel_hi:[1,0,1]
	global_store_dwordx4 v[142:143], v[192:195], off offset:576 sc1
	v_lshl_add_u64 v[142:143], v[140:141], 0, s[18:19]
	v_add_co_u32_e32 v140, vcc, s84, v140
	s_nop 1
	v_addc_co_u32_e32 v141, vcc, 0, v141, vcc
	global_load_dwordx4 v[150:153], v[140:141], off
	global_load_dwordx4 v[196:199], v[142:143], off offset:64
	global_load_dwordx4 v[200:203], v[142:143], off offset:512
	global_load_dwordx4 v[204:207], v[142:143], off offset:576
	s_waitcnt vmcnt(3) lgkmcnt(0)
	v_pk_fma_f32 v[152:153], v[14:15], 0.5, v[152:153] op_sel_hi:[1,0,1]
	v_pk_fma_f32 v[150:151], v[12:13], 0.5, v[150:151] op_sel_hi:[1,0,1]
	global_store_dwordx4 v[140:141], v[150:153], off sc1
	s_waitcnt vmcnt(3) lgkmcnt(0)
	v_pk_fma_f32 v[198:199], v[10:11], 0.5, v[198:199] op_sel_hi:[1,0,1]
	v_pk_fma_f32 v[196:197], v[8:9], 0.5, v[196:197] op_sel_hi:[1,0,1]
	global_store_dwordx4 v[142:143], v[196:199], off offset:64 sc1
	s_waitcnt vmcnt(3) lgkmcnt(0)
	v_pk_fma_f32 v[202:203], v[6:7], 0.5, v[202:203] op_sel_hi:[1,0,1]
	v_pk_fma_f32 v[200:201], v[4:5], 0.5, v[200:201] op_sel_hi:[1,0,1]
	global_store_dwordx4 v[142:143], v[200:203], off offset:512 sc1
	s_waitcnt vmcnt(3) lgkmcnt(0)
	v_pk_fma_f32 v[206:207], v[2:3], 0.5, v[206:207] op_sel_hi:[1,0,1]
	v_pk_fma_f32 v[204:205], v[0:1], 0.5, v[204:205] op_sel_hi:[1,0,1]
	global_store_dwordx4 v[142:143], v[204:207], off offset:576 sc1
	s_cbranch_execnz .LBB0_2895
.LBB0_2900:
	v_add_u32_e32 v140, 0xffff8000, v136
	s_lshl_b64 s[40:41], s[16:17], 23
	v_ashrrev_i32_e32 v141, 31, v140
	s_add_u32 s40, s62, s40
	s_addc_u32 s41, s63, s41
	v_lshlrev_b64 v[140:141], 12, v[140:141]
	v_lshl_add_u64 v[140:141], s[40:41], 0, v[140:141]
	v_lshlrev_b64 v[138:139], 2, v[138:139]
	v_lshl_add_u64 v[140:141], v[140:141], 0, v[138:139]
	global_store_dwordx4 v[140:141], v[124:127], off sc1
	global_store_dwordx4 v[140:141], v[120:123], off offset:64 sc1
	global_store_dwordx4 v[140:141], v[116:119], off offset:512 sc1
	global_store_dwordx4 v[140:141], v[112:115], off offset:576 sc1
	s_nop 1
	v_add_u32_e32 v112, 0xffff8010, v136
	v_ashrrev_i32_e32 v113, 31, v112
	v_lshlrev_b64 v[112:113], 12, v[112:113]
	v_lshl_add_u64 v[112:113], s[40:41], 0, v[112:113]
	v_lshl_add_u64 v[112:113], v[112:113], 0, v[138:139]
	global_store_dwordx4 v[112:113], v[108:111], off sc1
	global_store_dwordx4 v[112:113], v[104:107], off offset:64 sc1
	global_store_dwordx4 v[112:113], v[100:103], off offset:512 sc1
	global_store_dwordx4 v[112:113], v[96:99], off offset:576 sc1
	s_nop 1
	v_add_u32_e32 v96, 0xffff8020, v136
	v_ashrrev_i32_e32 v97, 31, v96
	v_lshlrev_b64 v[96:97], 12, v[96:97]
	v_lshl_add_u64 v[96:97], s[40:41], 0, v[96:97]
	v_lshl_add_u64 v[96:97], v[96:97], 0, v[138:139]
	global_store_dwordx4 v[96:97], v[92:95], off sc1
	global_store_dwordx4 v[96:97], v[88:91], off offset:64 sc1
	global_store_dwordx4 v[96:97], v[84:87], off offset:512 sc1
	global_store_dwordx4 v[96:97], v[80:83], off offset:576 sc1
	s_nop 1
	v_add_u32_e32 v80, 0xffff8030, v136
	v_ashrrev_i32_e32 v81, 31, v80
	v_lshlrev_b64 v[80:81], 12, v[80:81]
	v_lshl_add_u64 v[80:81], s[40:41], 0, v[80:81]
	v_lshl_add_u64 v[80:81], v[80:81], 0, v[138:139]
	global_store_dwordx4 v[80:81], v[76:79], off sc1
	global_store_dwordx4 v[80:81], v[72:75], off offset:64 sc1
	global_store_dwordx4 v[80:81], v[68:71], off offset:512 sc1
	global_store_dwordx4 v[80:81], v[64:67], off offset:576 sc1
	s_nop 1
	v_add_u32_e32 v64, 0xffff8080, v136
	v_ashrrev_i32_e32 v65, 31, v64
	v_lshlrev_b64 v[64:65], 12, v[64:65]
	v_lshl_add_u64 v[64:65], s[40:41], 0, v[64:65]
	v_lshl_add_u64 v[64:65], v[64:65], 0, v[138:139]
	global_store_dwordx4 v[64:65], v[60:63], off sc1
	global_store_dwordx4 v[64:65], v[56:59], off offset:64 sc1
	global_store_dwordx4 v[64:65], v[52:55], off offset:512 sc1
	global_store_dwordx4 v[64:65], v[48:51], off offset:576 sc1
	s_nop 1
	v_add_u32_e32 v48, 0xffff8090, v136
	v_ashrrev_i32_e32 v49, 31, v48
	v_lshlrev_b64 v[48:49], 12, v[48:49]
	v_lshl_add_u64 v[48:49], s[40:41], 0, v[48:49]
	v_lshl_add_u64 v[48:49], v[48:49], 0, v[138:139]
	global_store_dwordx4 v[48:49], v[44:47], off sc1
	global_store_dwordx4 v[48:49], v[40:43], off offset:64 sc1
	global_store_dwordx4 v[48:49], v[36:39], off offset:512 sc1
	global_store_dwordx4 v[48:49], v[32:35], off offset:576 sc1
	s_nop 1
	v_add_u32_e32 v32, 0xffff80a0, v136
	v_ashrrev_i32_e32 v33, 31, v32
	v_lshlrev_b64 v[32:33], 12, v[32:33]
	v_lshl_add_u64 v[32:33], s[40:41], 0, v[32:33]
	v_lshl_add_u64 v[32:33], v[32:33], 0, v[138:139]
	global_store_dwordx4 v[32:33], v[28:31], off sc1
	global_store_dwordx4 v[32:33], v[24:27], off offset:64 sc1
	global_store_dwordx4 v[32:33], v[20:23], off offset:512 sc1
	global_store_dwordx4 v[32:33], v[16:19], off offset:576 sc1
	s_nop 1
	v_add_u32_e32 v16, 0xffff80b0, v136
	v_ashrrev_i32_e32 v17, 31, v16
	v_lshlrev_b64 v[16:17], 12, v[16:17]
	v_lshl_add_u64 v[16:17], s[40:41], 0, v[16:17]
	v_lshl_add_u64 v[16:17], v[16:17], 0, v[138:139]
	global_store_dwordx4 v[16:17], v[12:15], off sc1
	global_store_dwordx4 v[16:17], v[8:11], off offset:64 sc1
	global_store_dwordx4 v[16:17], v[4:7], off offset:512 sc1
	global_store_dwordx4 v[16:17], v[0:3], off offset:576 sc1
	s_and_b64 vcc, exec, s[8:9]
	s_mov_b64 s[8:9], -1
	s_cbranch_vccnz .LBB0_2873
